# plus: drop the mid-block s_setprio 0/1 pairs inside each 32-MFMA stream
# baseline (speedup 1.0000x reference)
; #define PG8_STAGE(bufoff, gbase, voff) do { _Pragma("unroll") for (int _i = 0; _i < 2; ++_i) \
;         __builtin_amdgcn_global_load_lds((const unsigned*)((const char*)(gbase) + (voff)[_i]), (PG8_LAS unsigned*)(lds + (bufoff) + ldsw + _i * 8192), 16, 0, 0); } while (0)
; #define PG8_LDA(dst, b, h) do { _Pragma("unroll") for (int m = 0; m < 4; ++m) _Pragma("unroll") for (int k = 0; k < 2; ++k) dst[m][k] = *(const PG8_LAS bf16x8*)(lds + PG8_SA(b, h) + aoff + m * 2048 + k * 1024); } while (0)
; #define PG8_LDB(dst, b, h) do { _Pragma("unroll") for (int n = 0; n < 2; ++n) _Pragma("unroll") for (int k = 0; k < 2; ++k) dst[n][k] = *(const PG8_LAS bf16x8*)(lds + PG8_SB(b, h) + boff + n * 2048 + k * 1024); } while (0)
; #define PG8_MMA(ai, bj, At, Bt) do { __builtin_amdgcn_s_setprio(1); _Pragma("unroll") for (int m = 0; m < 4; ++m) _Pragma("unroll") for (int n = 0; n < 2; ++n) _Pragma("unroll") for (int k = 0; k < 2; ++k) \
;         acc[ai][bj][m][n] = __builtin_amdgcn_mfma_f32_16x16x32_bf16(Bt[n][k], At[m][k], acc[ai][bj][m][n], 0, 0, 0); __builtin_amdgcn_s_setprio(0); } while (0)
; #define PG8_WAIT_V(n) asm volatile("s_waitcnt vmcnt(" #n ")" ::: "memory")
; #define PG8_WAIT_L(n) asm volatile("s_waitcnt lgkmcnt(" #n ")" ::: "memory")
; template <class Epi, class Sched, bool ALIGN_EPI = false, bool SP2 = false>
; __device__ __forceinline__ void gemm_phase(PG8_LAS unsigned char* lds, const Gemm g, const Sched& S, const Epi& E) {
;     ...
;             const bool last = (t == nt - 2);
;             const char* a1 = cA + (size_t)(t + 1) * kstep;
;             const char* a2 = last ? nA : cA + (size_t)(t + 2) * kstep; const char* b2 = last ? nB : cB + (size_t)(t + 2) * kstep;
;             const char* a3 = a2 + kstep; const char* b3 = b2 + kstep;
;             if (last && has_next) S.a_ready(nxt);
;             if constexpr (SP2) {
;             PG8_LDB(B0, 0, 0); PG8_LDB(B1, 0, 1); PG8_SCHED; PG8_LDA(At, 0, 0); PG8_STAGE(PG8_SA(1, 1), a1 + hstep, voffA);
;             PG8_WAIT_V(8); PG8_WAIT_L(0); PG8_BAR; PG8_MMA(0, 0, At, B0); PG8_MMA(0, 1, At, B1); PG8_BAR; PG8_SCHED;
;             PG8_LDA(At, 0, 1); PG8_STAGE(PG8_SB(0, 0), b2, voffB); PG8_STAGE(PG8_SB(0, 1), b2 + hstep, voffB); PG8_STAGE(PG8_SA(0, 0), a2, voffA);
;             PG8_WAIT_V(8); PG8_WAIT_L(0); PG8_BAR; PG8_MMA(1, 0, At, B0); PG8_MMA(1, 1, At, B1); PG8_BAR; PG8_SCHED;
.LBB0_63:
	s_add_i32 s66, s46, 2
	s_add_u32 s10, s44, 0x80
	s_addc_u32 s11, s45, 0
	s_add_i32 s67, 0, 0x10000
	s_cmp_eq_u32 s74, s46
	s_cselect_b32 s47, s63, s11
	s_cselect_b32 s46, s62, s10
	s_cselect_b32 s79, s65, s20
	s_cselect_b32 s78, s64, s19
	s_add_i32 s10, 0, 0x14000
	v_add_u32_e32 v140, s67, v183
	v_add_u32_e32 v166, s10, v183
	ds_read_b128 v[128:131], v140
	ds_read_b128 v[132:135], v140 offset:1024
	ds_read_b128 v[136:139], v140 offset:2048
	ds_read_b128 v[140:143], v140 offset:3072
	ds_read_b128 v[144:147], v166
	ds_read_b128 v[148:151], v166 offset:1024
	ds_read_b128 v[152:155], v166 offset:2048
	ds_read_b128 v[166:169], v166 offset:3072
	v_lshl_add_u64 v[190:191], s[44:45], 0, v[162:163]
	s_add_i32 m0, s23, 0xc000
	ds_read_b128 v[170:173], v185
	ds_read_b128 v[174:177], v185 offset:1024
	ds_read_b128 v[178:181], v185 offset:2048
	ds_read_b128 v[186:189], v185 offset:3072
	ds_read_b128 v[194:197], v185 offset:4096
	ds_read_b128 v[198:201], v185 offset:5120
	ds_read_b128 v[202:205], v185 offset:6144
	ds_read_b128 v[206:209], v185 offset:7168
	global_load_lds_dwordx4 v[190:191], off
	v_lshl_add_u64 v[190:191], s[44:45], 0, v[164:165]
	s_add_i32 m0, s23, 0xe000
	s_nop 0
	global_load_lds_dwordx4 v[190:191], off
	s_waitcnt vmcnt(8)
	s_waitcnt lgkmcnt(0)
	s_setprio 1
	s_barrier
	v_mfma_f32_16x16x32_bf16 v[124:127], v[128:131], v[170:173], v[124:127]
	v_mfma_f32_16x16x32_bf16 v[120:123], v[136:139], v[170:173], v[120:123]
	v_mfma_f32_16x16x32_bf16 v[108:111], v[128:131], v[178:181], v[108:111]
	v_mfma_f32_16x16x32_bf16 v[104:107], v[136:139], v[178:181], v[104:107]
	v_mfma_f32_16x16x32_bf16 v[92:95], v[128:131], v[194:197], v[92:95]
	v_mfma_f32_16x16x32_bf16 v[88:91], v[136:139], v[194:197], v[88:91]
	v_mfma_f32_16x16x32_bf16 v[76:79], v[128:131], v[202:205], v[76:79]
	v_mfma_f32_16x16x32_bf16 v[72:75], v[136:139], v[202:205], v[72:75]
	v_mfma_f32_16x16x32_bf16 v[124:127], v[132:135], v[174:177], v[124:127]
	v_mfma_f32_16x16x32_bf16 v[120:123], v[140:143], v[174:177], v[120:123]
	v_mfma_f32_16x16x32_bf16 v[108:111], v[132:135], v[186:189], v[108:111]
	v_mfma_f32_16x16x32_bf16 v[104:107], v[140:143], v[186:189], v[104:107]
	v_mfma_f32_16x16x32_bf16 v[92:95], v[132:135], v[198:201], v[92:95]
	v_mfma_f32_16x16x32_bf16 v[88:91], v[140:143], v[198:201], v[88:91]
	v_mfma_f32_16x16x32_bf16 v[76:79], v[132:135], v[206:209], v[76:79]
	v_mfma_f32_16x16x32_bf16 v[72:75], v[140:143], v[206:209], v[72:75]
	v_mfma_f32_16x16x32_bf16 v[116:119], v[144:147], v[170:173], v[116:119]
	v_mfma_f32_16x16x32_bf16 v[112:115], v[152:155], v[170:173], v[112:115]
	v_mfma_f32_16x16x32_bf16 v[100:103], v[144:147], v[178:181], v[100:103]
	v_mfma_f32_16x16x32_bf16 v[96:99], v[152:155], v[178:181], v[96:99]
	v_mfma_f32_16x16x32_bf16 v[84:87], v[144:147], v[194:197], v[84:87]
	v_mfma_f32_16x16x32_bf16 v[80:83], v[152:155], v[194:197], v[80:83]
	v_mfma_f32_16x16x32_bf16 v[68:71], v[144:147], v[202:205], v[68:71]
	v_mfma_f32_16x16x32_bf16 v[64:67], v[152:155], v[202:205], v[64:67]
	v_mfma_f32_16x16x32_bf16 v[116:119], v[148:151], v[174:177], v[116:119]
	v_mfma_f32_16x16x32_bf16 v[112:115], v[166:169], v[174:177], v[112:115]
	v_mfma_f32_16x16x32_bf16 v[100:103], v[148:151], v[186:189], v[100:103]
	v_mfma_f32_16x16x32_bf16 v[96:99], v[166:169], v[186:189], v[96:99]
	v_mfma_f32_16x16x32_bf16 v[84:87], v[148:151], v[198:201], v[84:87]
	v_mfma_f32_16x16x32_bf16 v[80:83], v[166:169], v[198:201], v[80:83]
	v_mfma_f32_16x16x32_bf16 v[68:71], v[148:151], v[206:209], v[68:71]
	v_mfma_f32_16x16x32_bf16 v[64:67], v[166:169], v[206:209], v[64:67]
	s_barrier
	s_setprio 0
	s_add_i32 s11, s67, s22
	v_lshl_add_u64 v[190:191], s[78:79], 0, v[192:193]
	s_mov_b32 m0, s11
	ds_read_b128 v[170:173], v185 offset:16384
	ds_read_b128 v[174:177], v185 offset:17408
	ds_read_b128 v[178:181], v185 offset:18432
	ds_read_b128 v[186:189], v185 offset:19456
	ds_read_b128 v[194:197], v185 offset:20480
	ds_read_b128 v[198:201], v185 offset:21504
	ds_read_b128 v[202:205], v185 offset:22528
	ds_read_b128 v[206:209], v185 offset:23552
	global_load_lds_dwordx4 v[190:191], off
	s_add_i32 m0, s11, 0x2000
	v_lshl_add_u64 v[210:211], s[78:79], 0, v[160:161]
	s_add_u32 s78, s78, s52
	s_addc_u32 s79, s79, 0
	s_add_i32 s10, s10, s22
	global_load_lds_dwordx4 v[210:211], off
	v_lshl_add_u64 v[212:213], s[78:79], 0, v[192:193]
	s_mov_b32 m0, s10
	v_lshl_add_u64 v[214:215], s[78:79], 0, v[160:161]
	global_load_lds_dwordx4 v[212:213], off
	s_add_i32 m0, s10, 0x2000
	v_lshl_add_u64 v[216:217], s[46:47], 0, v[156:157]
	global_load_lds_dwordx4 v[214:215], off
	s_mov_b32 m0, s23
	v_lshl_add_u64 v[218:219], s[46:47], 0, v[158:159]
	global_load_lds_dwordx4 v[216:217], off
	s_mov_b32 m0, s51
	s_nop 0
	global_load_lds_dwordx4 v[218:219], off
	s_waitcnt vmcnt(8)
	s_waitcnt lgkmcnt(0)
	s_setprio 1
	s_barrier
; #define PG8_STAGE(bufoff, gbase, voff) do { _Pragma("unroll") for (int _i = 0; _i < 2; ++_i) \
;         __builtin_amdgcn_global_load_lds((const unsigned*)((const char*)(gbase) + (voff)[_i]), (PG8_LAS unsigned*)(lds + (bufoff) + ldsw + _i * 8192), 16, 0, 0); } while (0)
; #define PG8_LDA(dst, b, h) do { _Pragma("unroll") for (int m = 0; m < 4; ++m) _Pragma("unroll") for (int k = 0; k < 2; ++k) dst[m][k] = *(const PG8_LAS bf16x8*)(lds + PG8_SA(b, h) + aoff + m * 2048 + k * 1024); } while (0)
; #define PG8_LDB(dst, b, h) do { _Pragma("unroll") for (int n = 0; n < 2; ++n) _Pragma("unroll") for (int k = 0; k < 2; ++k) dst[n][k] = *(const PG8_LAS bf16x8*)(lds + PG8_SB(b, h) + boff + n * 2048 + k * 1024); } while (0)
; #define PG8_MMA(ai, bj, At, Bt) do { __builtin_amdgcn_s_setprio(1); _Pragma("unroll") for (int m = 0; m < 4; ++m) _Pragma("unroll") for (int n = 0; n < 2; ++n) _Pragma("unroll") for (int k = 0; k < 2; ++k) \
;         acc[ai][bj][m][n] = __builtin_amdgcn_mfma_f32_16x16x32_bf16(Bt[n][k], At[m][k], acc[ai][bj][m][n], 0, 0, 0); __builtin_amdgcn_s_setprio(0); } while (0)
; #define PG8_WAIT_V(n) asm volatile("s_waitcnt vmcnt(" #n ")" ::: "memory")
; #define PG8_WAIT_L(n) asm volatile("s_waitcnt lgkmcnt(" #n ")" ::: "memory")
; #define PG8_BAR __builtin_amdgcn_s_barrier()
; #define PG8_SCHED __builtin_amdgcn_sched_barrier(0)
; template <class Epi, class Sched, bool ALIGN_EPI = false, bool SP2 = false>
; __device__ __forceinline__ void gemm_phase(PG8_LAS unsigned char* lds, const Gemm g, const Sched& S, const Epi& E) {
;     ...
;             PG8_WAIT_V(8); PG8_WAIT_L(0); PG8_BAR; PG8_MMA(1, 0, At, B0); PG8_MMA(1, 1, At, B1); PG8_BAR; PG8_SCHED;
;             PG8_LDB(B0, 1, 0); PG8_LDB(B1, 1, 1); PG8_SCHED; PG8_LDA(At, 1, 0); PG8_STAGE(PG8_SA(0, 1), a2 + hstep, voffA);
;             PG8_WAIT_V(8); PG8_WAIT_L(0); PG8_BAR; PG8_MMA(0, 0, At, B0); PG8_MMA(0, 1, At, B1); PG8_BAR; PG8_SCHED;
	v_mfma_f32_16x16x32_bf16 v[60:63], v[128:131], v[170:173], v[60:63]
	v_mfma_f32_16x16x32_bf16 v[56:59], v[136:139], v[170:173], v[56:59]
	v_mfma_f32_16x16x32_bf16 v[44:47], v[128:131], v[178:181], v[44:47]
	v_mfma_f32_16x16x32_bf16 v[40:43], v[136:139], v[178:181], v[40:43]
	v_mfma_f32_16x16x32_bf16 v[28:31], v[128:131], v[194:197], v[28:31]
	v_mfma_f32_16x16x32_bf16 v[24:27], v[136:139], v[194:197], v[24:27]
	v_mfma_f32_16x16x32_bf16 v[12:15], v[128:131], v[202:205], v[12:15]
	v_mfma_f32_16x16x32_bf16 v[8:11], v[136:139], v[202:205], v[8:11]
	v_mfma_f32_16x16x32_bf16 v[60:63], v[132:135], v[174:177], v[60:63]
	v_mfma_f32_16x16x32_bf16 v[56:59], v[140:143], v[174:177], v[56:59]
	v_mfma_f32_16x16x32_bf16 v[44:47], v[132:135], v[186:189], v[44:47]
	v_mfma_f32_16x16x32_bf16 v[40:43], v[140:143], v[186:189], v[40:43]
	v_mfma_f32_16x16x32_bf16 v[28:31], v[132:135], v[198:201], v[28:31]
	v_mfma_f32_16x16x32_bf16 v[24:27], v[140:143], v[198:201], v[24:27]
	v_mfma_f32_16x16x32_bf16 v[12:15], v[132:135], v[206:209], v[12:15]
	v_mfma_f32_16x16x32_bf16 v[8:11], v[140:143], v[206:209], v[8:11]
	v_mfma_f32_16x16x32_bf16 v[52:55], v[144:147], v[170:173], v[52:55]
	v_mfma_f32_16x16x32_bf16 v[48:51], v[152:155], v[170:173], v[48:51]
	v_mfma_f32_16x16x32_bf16 v[36:39], v[144:147], v[178:181], v[36:39]
	v_mfma_f32_16x16x32_bf16 v[32:35], v[152:155], v[178:181], v[32:35]
	v_mfma_f32_16x16x32_bf16 v[20:23], v[144:147], v[194:197], v[20:23]
	v_mfma_f32_16x16x32_bf16 v[16:19], v[152:155], v[194:197], v[16:19]
	v_mfma_f32_16x16x32_bf16 v[4:7], v[144:147], v[202:205], v[4:7]
	v_mfma_f32_16x16x32_bf16 v[0:3], v[152:155], v[202:205], v[0:3]
	v_mfma_f32_16x16x32_bf16 v[52:55], v[148:151], v[174:177], v[52:55]
	v_mfma_f32_16x16x32_bf16 v[48:51], v[166:169], v[174:177], v[48:51]
	v_mfma_f32_16x16x32_bf16 v[36:39], v[148:151], v[186:189], v[36:39]
	v_mfma_f32_16x16x32_bf16 v[32:35], v[166:169], v[186:189], v[32:35]
	v_mfma_f32_16x16x32_bf16 v[20:23], v[148:151], v[198:201], v[20:23]
	v_mfma_f32_16x16x32_bf16 v[16:19], v[166:169], v[198:201], v[16:19]
	v_mfma_f32_16x16x32_bf16 v[4:7], v[148:151], v[206:209], v[4:7]
	v_mfma_f32_16x16x32_bf16 v[0:3], v[166:169], v[206:209], v[0:3]
	s_barrier
	s_setprio 0
	s_add_i32 s10, 0, 0x18000
	s_add_i32 s11, 0, 0x1c000
	v_add_u32_e32 v140, s10, v183
	v_add_u32_e32 v166, s11, v183
	ds_read_b128 v[128:131], v140
	ds_read_b128 v[132:135], v140 offset:1024
	ds_read_b128 v[136:139], v140 offset:2048
	ds_read_b128 v[140:143], v140 offset:3072
	ds_read_b128 v[144:147], v166
	ds_read_b128 v[148:151], v166 offset:1024
	ds_read_b128 v[152:155], v166 offset:2048
	ds_read_b128 v[166:169], v166 offset:3072
	s_add_u32 s46, s46, s52
	s_addc_u32 s47, s47, 0
	s_mov_b32 m0, s68
	v_lshl_add_u64 v[220:221], s[46:47], 0, v[156:157]
	ds_read_b128 v[170:173], v185 offset:32768
	ds_read_b128 v[174:177], v185 offset:33792
	ds_read_b128 v[178:181], v185 offset:34816
	ds_read_b128 v[186:189], v185 offset:35840
	ds_read_b128 v[194:197], v185 offset:36864
	ds_read_b128 v[198:201], v185 offset:37888
	ds_read_b128 v[202:205], v185 offset:38912
	ds_read_b128 v[206:209], v185 offset:39936
	global_load_lds_dwordx4 v[220:221], off
	v_lshl_add_u64 v[220:221], s[46:47], 0, v[158:159]
	s_mov_b32 m0, s69
	s_nop 0
	global_load_lds_dwordx4 v[220:221], off
	s_waitcnt vmcnt(8)
	s_waitcnt lgkmcnt(0)
	s_setprio 1
	s_barrier
	v_mfma_f32_16x16x32_bf16 v[124:127], v[128:131], v[170:173], v[124:127]
	v_mfma_f32_16x16x32_bf16 v[120:123], v[136:139], v[170:173], v[120:123]
	v_mfma_f32_16x16x32_bf16 v[108:111], v[128:131], v[178:181], v[108:111]
	v_mfma_f32_16x16x32_bf16 v[104:107], v[136:139], v[178:181], v[104:107]
	v_mfma_f32_16x16x32_bf16 v[92:95], v[128:131], v[194:197], v[92:95]
	v_mfma_f32_16x16x32_bf16 v[88:91], v[136:139], v[194:197], v[88:91]
	v_mfma_f32_16x16x32_bf16 v[76:79], v[128:131], v[202:205], v[76:79]
	v_mfma_f32_16x16x32_bf16 v[72:75], v[136:139], v[202:205], v[72:75]
	v_mfma_f32_16x16x32_bf16 v[124:127], v[132:135], v[174:177], v[124:127]
	v_mfma_f32_16x16x32_bf16 v[120:123], v[140:143], v[174:177], v[120:123]
	v_mfma_f32_16x16x32_bf16 v[108:111], v[132:135], v[186:189], v[108:111]
	v_mfma_f32_16x16x32_bf16 v[104:107], v[140:143], v[186:189], v[104:107]
	v_mfma_f32_16x16x32_bf16 v[92:95], v[132:135], v[198:201], v[92:95]
	v_mfma_f32_16x16x32_bf16 v[88:91], v[140:143], v[198:201], v[88:91]
	v_mfma_f32_16x16x32_bf16 v[76:79], v[132:135], v[206:209], v[76:79]
	v_mfma_f32_16x16x32_bf16 v[72:75], v[140:143], v[206:209], v[72:75]
	v_mfma_f32_16x16x32_bf16 v[116:119], v[144:147], v[170:173], v[116:119]
	v_mfma_f32_16x16x32_bf16 v[112:115], v[152:155], v[170:173], v[112:115]
	v_mfma_f32_16x16x32_bf16 v[100:103], v[144:147], v[178:181], v[100:103]
	v_mfma_f32_16x16x32_bf16 v[96:99], v[152:155], v[178:181], v[96:99]
	v_mfma_f32_16x16x32_bf16 v[84:87], v[144:147], v[194:197], v[84:87]
	v_mfma_f32_16x16x32_bf16 v[80:83], v[152:155], v[194:197], v[80:83]
	v_mfma_f32_16x16x32_bf16 v[68:71], v[144:147], v[202:205], v[68:71]
	v_mfma_f32_16x16x32_bf16 v[64:67], v[152:155], v[202:205], v[64:67]
	v_mfma_f32_16x16x32_bf16 v[116:119], v[148:151], v[174:177], v[116:119]
	v_mfma_f32_16x16x32_bf16 v[112:115], v[166:169], v[174:177], v[112:115]
	v_mfma_f32_16x16x32_bf16 v[100:103], v[148:151], v[186:189], v[100:103]
	v_mfma_f32_16x16x32_bf16 v[96:99], v[166:169], v[186:189], v[96:99]
	v_mfma_f32_16x16x32_bf16 v[84:87], v[148:151], v[198:201], v[84:87]
	v_mfma_f32_16x16x32_bf16 v[80:83], v[166:169], v[198:201], v[80:83]
	v_mfma_f32_16x16x32_bf16 v[68:71], v[148:151], v[206:209], v[68:71]
	v_mfma_f32_16x16x32_bf16 v[64:67], v[166:169], v[206:209], v[64:67]
	s_barrier
; #define PG8_STAGE(bufoff, gbase, voff) do { _Pragma("unroll") for (int _i = 0; _i < 2; ++_i) \
;         __builtin_amdgcn_global_load_lds((const unsigned*)((const char*)(gbase) + (voff)[_i]), (PG8_LAS unsigned*)(lds + (bufoff) + ldsw + _i * 8192), 16, 0, 0); } while (0)
; #define PG8_LDA(dst, b, h) do { _Pragma("unroll") for (int m = 0; m < 4; ++m) _Pragma("unroll") for (int k = 0; k < 2; ++k) dst[m][k] = *(const PG8_LAS bf16x8*)(lds + PG8_SA(b, h) + aoff + m * 2048 + k * 1024); } while (0)
; #define PG8_MMA(ai, bj, At, Bt) do { __builtin_amdgcn_s_setprio(1); _Pragma("unroll") for (int m = 0; m < 4; ++m) _Pragma("unroll") for (int n = 0; n < 2; ++n) _Pragma("unroll") for (int k = 0; k < 2; ++k) \
;         acc[ai][bj][m][n] = __builtin_amdgcn_mfma_f32_16x16x32_bf16(Bt[n][k], At[m][k], acc[ai][bj][m][n], 0, 0, 0); __builtin_amdgcn_s_setprio(0); } while (0)
; #define PG8_WAIT_V(n) asm volatile("s_waitcnt vmcnt(" #n ")" ::: "memory")
; #define PG8_WAIT_L(n) asm volatile("s_waitcnt lgkmcnt(" #n ")" ::: "memory")
; #define PG8_BAR __builtin_amdgcn_s_barrier()
; #define PG8_SCHED __builtin_amdgcn_sched_barrier(0)
; template <class Epi, class Sched, bool ALIGN_EPI = false, bool SP2 = false>
; __device__ __forceinline__ void gemm_phase(PG8_LAS unsigned char* lds, const Gemm g, const Sched& S, const Epi& E) {
;     ...
;         for (int t = 0; t < nt; t += 2) {
;             const bool last = (t == nt - 2);
;             const char* a1 = cA + (size_t)(t + 1) * kstep;
;     ...
;             PG8_LDA(At, 1, 1); PG8_STAGE(PG8_SB(1, 0), b3, voffB); PG8_STAGE(PG8_SB(1, 1), b3 + hstep, voffB); PG8_STAGE(PG8_SA(1, 0), a3, voffA);
;             PG8_WAIT_V(8); PG8_WAIT_L(0); PG8_BAR; PG8_MMA(1, 0, At, B0); PG8_MMA(1, 1, At, B1); PG8_BAR; PG8_SCHED;
	s_setprio 0
	s_add_i32 s10, s10, s22
	v_lshl_add_u64 v[190:191], v[190:191], 0, s[36:37]
	s_mov_b32 m0, s10
	ds_read_b128 v[170:173], v185 offset:49152
	ds_read_b128 v[174:177], v185 offset:50176
	ds_read_b128 v[178:181], v185 offset:51200
	ds_read_b128 v[186:189], v185 offset:52224
	ds_read_b128 v[194:197], v185 offset:53248
	ds_read_b128 v[198:201], v185 offset:54272
	ds_read_b128 v[202:205], v185 offset:55296
	ds_read_b128 v[206:209], v185 offset:56320
	global_load_lds_dwordx4 v[190:191], off
	v_lshl_add_u64 v[190:191], v[210:211], 0, s[36:37]
	s_add_i32 m0, s10, 0x2000
	s_add_i32 s10, s11, s22
	global_load_lds_dwordx4 v[190:191], off
	v_lshl_add_u64 v[190:191], v[212:213], 0, s[36:37]
	s_mov_b32 m0, s10
	s_nop 0
	global_load_lds_dwordx4 v[190:191], off
	v_lshl_add_u64 v[190:191], v[214:215], 0, s[36:37]
	s_add_i32 m0, s10, 0x2000
	s_nop 0
	global_load_lds_dwordx4 v[190:191], off
	v_lshl_add_u64 v[190:191], v[216:217], 0, s[36:37]
	s_mov_b32 m0, s70
	s_nop 0
	global_load_lds_dwordx4 v[190:191], off
	v_lshl_add_u64 v[190:191], v[218:219], 0, s[36:37]
	s_mov_b32 m0, s71
	s_nop 0
	global_load_lds_dwordx4 v[190:191], off
	s_waitcnt vmcnt(8)
	s_waitcnt lgkmcnt(0)
	s_setprio 1
	s_barrier
	v_mfma_f32_16x16x32_bf16 v[60:63], v[128:131], v[170:173], v[60:63]
	v_mfma_f32_16x16x32_bf16 v[56:59], v[136:139], v[170:173], v[56:59]
	v_mfma_f32_16x16x32_bf16 v[44:47], v[128:131], v[178:181], v[44:47]
	v_mfma_f32_16x16x32_bf16 v[40:43], v[136:139], v[178:181], v[40:43]
	v_mfma_f32_16x16x32_bf16 v[28:31], v[128:131], v[194:197], v[28:31]
	v_mfma_f32_16x16x32_bf16 v[24:27], v[136:139], v[194:197], v[24:27]
	v_mfma_f32_16x16x32_bf16 v[12:15], v[128:131], v[202:205], v[12:15]
	v_mfma_f32_16x16x32_bf16 v[8:11], v[136:139], v[202:205], v[8:11]
	v_mfma_f32_16x16x32_bf16 v[60:63], v[132:135], v[174:177], v[60:63]
	v_mfma_f32_16x16x32_bf16 v[56:59], v[140:143], v[174:177], v[56:59]
	v_mfma_f32_16x16x32_bf16 v[44:47], v[132:135], v[186:189], v[44:47]
	v_mfma_f32_16x16x32_bf16 v[40:43], v[140:143], v[186:189], v[40:43]
	v_mfma_f32_16x16x32_bf16 v[28:31], v[132:135], v[198:201], v[28:31]
	v_mfma_f32_16x16x32_bf16 v[24:27], v[140:143], v[198:201], v[24:27]
	v_mfma_f32_16x16x32_bf16 v[12:15], v[132:135], v[206:209], v[12:15]
	v_mfma_f32_16x16x32_bf16 v[8:11], v[140:143], v[206:209], v[8:11]
	v_mfma_f32_16x16x32_bf16 v[52:55], v[144:147], v[170:173], v[52:55]
	v_mfma_f32_16x16x32_bf16 v[48:51], v[152:155], v[170:173], v[48:51]
	v_mfma_f32_16x16x32_bf16 v[36:39], v[144:147], v[178:181], v[36:39]
	v_mfma_f32_16x16x32_bf16 v[32:35], v[152:155], v[178:181], v[32:35]
	v_mfma_f32_16x16x32_bf16 v[20:23], v[144:147], v[194:197], v[20:23]
	v_mfma_f32_16x16x32_bf16 v[16:19], v[152:155], v[194:197], v[16:19]
	v_mfma_f32_16x16x32_bf16 v[4:7], v[144:147], v[202:205], v[4:7]
	v_mfma_f32_16x16x32_bf16 v[0:3], v[152:155], v[202:205], v[0:3]
	v_mfma_f32_16x16x32_bf16 v[52:55], v[148:151], v[174:177], v[52:55]
	v_mfma_f32_16x16x32_bf16 v[48:51], v[166:169], v[174:177], v[48:51]
	v_mfma_f32_16x16x32_bf16 v[36:39], v[148:151], v[186:189], v[36:39]
	v_mfma_f32_16x16x32_bf16 v[32:35], v[166:169], v[186:189], v[32:35]
	v_mfma_f32_16x16x32_bf16 v[20:23], v[148:151], v[198:201], v[20:23]
	v_mfma_f32_16x16x32_bf16 v[16:19], v[166:169], v[198:201], v[16:19]
	v_mfma_f32_16x16x32_bf16 v[4:7], v[148:151], v[206:209], v[4:7]
	v_mfma_f32_16x16x32_bf16 v[0:3], v[166:169], v[206:209], v[0:3]
	s_barrier
	s_setprio 0
	s_add_u32 s44, s44, 0x100
	s_addc_u32 s45, s45, 0
	s_add_u32 s19, s19, 0x100
	s_addc_u32 s20, s20, 0
	s_cmp_ge_u32 s66, s73
	s_mov_b32 s46, s66
	s_cbranch_scc0 .LBB0_63
	s_and_b64 vcc, exec, s[56:57]
	s_cbranch_vccz .LBB0_66
	s_barrier

; #define PG8_STAGE(bufoff, gbase, voff) do { _Pragma("unroll") for (int _i = 0; _i < 2; ++_i) \
;         __builtin_amdgcn_global_load_lds((const unsigned*)((const char*)(gbase) + (voff)[_i]), (PG8_LAS unsigned*)(lds + (bufoff) + ldsw + _i * 8192), 16, 0, 0); } while (0)
; #define PG8_LDA(dst, b, h) do { _Pragma("unroll") for (int m = 0; m < 4; ++m) _Pragma("unroll") for (int k = 0; k < 2; ++k) dst[m][k] = *(const PG8_LAS bf16x8*)(lds + PG8_SA(b, h) + aoff + m * 2048 + k * 1024); } while (0)
; #define PG8_LDB(dst, b, h) do { _Pragma("unroll") for (int n = 0; n < 2; ++n) _Pragma("unroll") for (int k = 0; k < 2; ++k) dst[n][k] = *(const PG8_LAS bf16x8*)(lds + PG8_SB(b, h) + boff + n * 2048 + k * 1024); } while (0)
; #define PG8_MMA(ai, bj, At, Bt) do { __builtin_amdgcn_s_setprio(1); _Pragma("unroll") for (int m = 0; m < 4; ++m) _Pragma("unroll") for (int n = 0; n < 2; ++n) _Pragma("unroll") for (int k = 0; k < 2; ++k) \
;         acc[ai][bj][m][n] = __builtin_amdgcn_mfma_f32_16x16x32_bf16(Bt[n][k], At[m][k], acc[ai][bj][m][n], 0, 0, 0); __builtin_amdgcn_s_setprio(0); } while (0)
; #define PG8_WAIT_V(n) asm volatile("s_waitcnt vmcnt(" #n ")" ::: "memory")
; #define PG8_WAIT_L(n) asm volatile("s_waitcnt lgkmcnt(" #n ")" ::: "memory")
; template <class Epi, class Sched, bool ALIGN_EPI = false, bool SP2 = false>
; __device__ __forceinline__ void gemm_phase(PG8_LAS unsigned char* lds, const Gemm g, const Sched& S, const Epi& E) {
;     ...
;             const bool last = (t == nt - 2);
;             const char* a1 = cA + (size_t)(t + 1) * kstep;
;             const char* a2 = last ? nA : cA + (size_t)(t + 2) * kstep; const char* b2 = last ? nB : cB + (size_t)(t + 2) * kstep;
;             const char* a3 = a2 + kstep; const char* b3 = b2 + kstep;
;             if (last && has_next) S.a_ready(nxt);
;             if constexpr (SP2) {
;             PG8_LDB(B0, 0, 0); PG8_LDB(B1, 0, 1); PG8_SCHED; PG8_LDA(At, 0, 0); PG8_STAGE(PG8_SA(1, 1), a1 + hstep, voffA);
;             PG8_WAIT_V(8); PG8_WAIT_L(0); PG8_BAR; PG8_MMA(0, 0, At, B0); PG8_MMA(0, 1, At, B1); PG8_BAR; PG8_SCHED;
;             PG8_LDA(At, 0, 1); PG8_STAGE(PG8_SB(0, 0), b2, voffB); PG8_STAGE(PG8_SB(0, 1), b2 + hstep, voffB); PG8_STAGE(PG8_SA(0, 0), a2, voffA);
;             PG8_WAIT_V(8); PG8_WAIT_L(0); PG8_BAR; PG8_MMA(1, 0, At, B0); PG8_MMA(1, 1, At, B1); PG8_BAR; PG8_SCHED;
.LBB0_200:
	s_add_u32 s10, s56, 0xfffc0080
	s_addc_u32 s11, s57, -1
	s_add_i32 s77, 0, 0x10000
	s_cmp_eq_u32 s76, 12
	s_cselect_b32 s61, s18, s11
	s_cselect_b32 s60, s19, s10
	s_cselect_b32 s59, s20, s51
	s_cselect_b32 s58, s43, s49
	s_add_i32 s10, 0, 0x14000
	v_add_u32_e32 v140, s77, v163
	v_add_u32_e32 v162, s10, v163
	ds_read_b128 v[128:131], v140
	ds_read_b128 v[132:135], v140 offset:1024
	ds_read_b128 v[136:139], v140 offset:2048
	ds_read_b128 v[140:143], v140 offset:3072
	ds_read_b128 v[166:169], v162
	ds_read_b128 v[170:173], v162 offset:1024
	ds_read_b128 v[174:177], v162 offset:2048
	ds_read_b128 v[178:181], v162 offset:3072
	v_lshl_add_u64 v[190:191], s[56:57], 0, v[158:159]
	s_add_i32 m0, s64, 0xc000
	ds_read_b128 v[182:185], v165
	ds_read_b128 v[186:189], v165 offset:1024
	ds_read_b128 v[194:197], v165 offset:2048
	ds_read_b128 v[198:201], v165 offset:3072
	ds_read_b128 v[202:205], v165 offset:4096
	ds_read_b128 v[206:209], v165 offset:5120
	ds_read_b128 v[210:213], v165 offset:6144
	ds_read_b128 v[214:217], v165 offset:7168
	global_load_lds_dwordx4 v[190:191], off
	v_lshl_add_u64 v[190:191], s[56:57], 0, v[160:161]
	s_add_i32 m0, s64, 0xe000
	s_nop 0
	global_load_lds_dwordx4 v[190:191], off
	s_waitcnt vmcnt(8)
	s_waitcnt lgkmcnt(0)
	s_setprio 1
	s_barrier
	v_mfma_f32_16x16x32_bf16 v[124:127], v[128:131], v[182:185], v[124:127]
	v_mfma_f32_16x16x32_bf16 v[120:123], v[136:139], v[182:185], v[120:123]
	v_mfma_f32_16x16x32_bf16 v[112:115], v[128:131], v[194:197], v[112:115]
	v_mfma_f32_16x16x32_bf16 v[104:107], v[136:139], v[194:197], v[104:107]
	v_mfma_f32_16x16x32_bf16 v[96:99], v[128:131], v[202:205], v[96:99]
	v_mfma_f32_16x16x32_bf16 v[88:91], v[136:139], v[202:205], v[88:91]
	v_mfma_f32_16x16x32_bf16 v[80:83], v[128:131], v[210:213], v[80:83]
	v_mfma_f32_16x16x32_bf16 v[72:75], v[136:139], v[210:213], v[72:75]
	v_mfma_f32_16x16x32_bf16 v[124:127], v[132:135], v[186:189], v[124:127]
	v_mfma_f32_16x16x32_bf16 v[120:123], v[140:143], v[186:189], v[120:123]
	v_mfma_f32_16x16x32_bf16 v[112:115], v[132:135], v[198:201], v[112:115]
	v_mfma_f32_16x16x32_bf16 v[104:107], v[140:143], v[198:201], v[104:107]
	v_mfma_f32_16x16x32_bf16 v[96:99], v[132:135], v[206:209], v[96:99]
	v_mfma_f32_16x16x32_bf16 v[88:91], v[140:143], v[206:209], v[88:91]
	v_mfma_f32_16x16x32_bf16 v[80:83], v[132:135], v[214:217], v[80:83]
	v_mfma_f32_16x16x32_bf16 v[72:75], v[140:143], v[214:217], v[72:75]
	v_mfma_f32_16x16x32_bf16 v[116:119], v[166:169], v[182:185], v[116:119]
	v_mfma_f32_16x16x32_bf16 v[108:111], v[174:177], v[182:185], v[108:111]
	v_mfma_f32_16x16x32_bf16 v[100:103], v[166:169], v[194:197], v[100:103]
	v_mfma_f32_16x16x32_bf16 v[92:95], v[174:177], v[194:197], v[92:95]
	v_mfma_f32_16x16x32_bf16 v[84:87], v[166:169], v[202:205], v[84:87]
	v_mfma_f32_16x16x32_bf16 v[76:79], v[174:177], v[202:205], v[76:79]
	v_mfma_f32_16x16x32_bf16 v[68:71], v[166:169], v[210:213], v[68:71]
	v_mfma_f32_16x16x32_bf16 v[64:67], v[174:177], v[210:213], v[64:67]
	v_mfma_f32_16x16x32_bf16 v[116:119], v[170:173], v[186:189], v[116:119]
	v_mfma_f32_16x16x32_bf16 v[108:111], v[178:181], v[186:189], v[108:111]
	v_mfma_f32_16x16x32_bf16 v[100:103], v[170:173], v[198:201], v[100:103]
	v_mfma_f32_16x16x32_bf16 v[92:95], v[178:181], v[198:201], v[92:95]
	v_mfma_f32_16x16x32_bf16 v[84:87], v[170:173], v[206:209], v[84:87]
	v_mfma_f32_16x16x32_bf16 v[76:79], v[178:181], v[206:209], v[76:79]
	v_mfma_f32_16x16x32_bf16 v[68:71], v[170:173], v[214:217], v[68:71]
	v_mfma_f32_16x16x32_bf16 v[64:67], v[178:181], v[214:217], v[64:67]
	s_barrier
	s_setprio 0
	s_add_i32 s11, s77, s63
	v_lshl_add_u64 v[190:191], s[58:59], 0, v[146:147]
	s_mov_b32 m0, s11
	ds_read_b128 v[182:185], v165 offset:16384
	ds_read_b128 v[186:189], v165 offset:17408
	ds_read_b128 v[194:197], v165 offset:18432
	ds_read_b128 v[198:201], v165 offset:19456
	ds_read_b128 v[202:205], v165 offset:20480
	ds_read_b128 v[206:209], v165 offset:21504
	ds_read_b128 v[210:213], v165 offset:22528
	ds_read_b128 v[214:217], v165 offset:23552
	global_load_lds_dwordx4 v[190:191], off
	s_add_i32 m0, s11, 0x2000
	s_add_u32 s78, s58, 0x40000
	v_lshl_add_u64 v[218:219], s[58:59], 0, v[150:151]
	s_addc_u32 s79, s59, 0
	s_add_i32 s10, s10, s63
	global_load_lds_dwordx4 v[218:219], off
	v_lshl_add_u64 v[220:221], s[78:79], 0, v[146:147]
	s_mov_b32 m0, s10
	v_lshl_add_u64 v[222:223], s[60:61], 0, v[148:149]
	global_load_lds_dwordx4 v[220:221], off
	v_lshl_add_u64 v[220:221], s[78:79], 0, v[150:151]
	s_add_i32 m0, s10, 0x2000
	s_nop 0
	global_load_lds_dwordx4 v[220:221], off
	v_lshl_add_u64 v[220:221], s[60:61], 0, v[144:145]
	s_mov_b32 m0, s64
	s_nop 0
	global_load_lds_dwordx4 v[220:221], off
	s_mov_b32 m0, s65
	s_nop 0
	global_load_lds_dwordx4 v[222:223], off
	s_waitcnt vmcnt(8)
	s_waitcnt lgkmcnt(0)
	s_setprio 1
	s_barrier
; #define PG8_STAGE(bufoff, gbase, voff) do { _Pragma("unroll") for (int _i = 0; _i < 2; ++_i) \
;         __builtin_amdgcn_global_load_lds((const unsigned*)((const char*)(gbase) + (voff)[_i]), (PG8_LAS unsigned*)(lds + (bufoff) + ldsw + _i * 8192), 16, 0, 0); } while (0)
; #define PG8_LDA(dst, b, h) do { _Pragma("unroll") for (int m = 0; m < 4; ++m) _Pragma("unroll") for (int k = 0; k < 2; ++k) dst[m][k] = *(const PG8_LAS bf16x8*)(lds + PG8_SA(b, h) + aoff + m * 2048 + k * 1024); } while (0)
; #define PG8_LDB(dst, b, h) do { _Pragma("unroll") for (int n = 0; n < 2; ++n) _Pragma("unroll") for (int k = 0; k < 2; ++k) dst[n][k] = *(const PG8_LAS bf16x8*)(lds + PG8_SB(b, h) + boff + n * 2048 + k * 1024); } while (0)
; #define PG8_MMA(ai, bj, At, Bt) do { __builtin_amdgcn_s_setprio(1); _Pragma("unroll") for (int m = 0; m < 4; ++m) _Pragma("unroll") for (int n = 0; n < 2; ++n) _Pragma("unroll") for (int k = 0; k < 2; ++k) \
;         acc[ai][bj][m][n] = __builtin_amdgcn_mfma_f32_16x16x32_bf16(Bt[n][k], At[m][k], acc[ai][bj][m][n], 0, 0, 0); __builtin_amdgcn_s_setprio(0); } while (0)
; #define PG8_WAIT_V(n) asm volatile("s_waitcnt vmcnt(" #n ")" ::: "memory")
; #define PG8_WAIT_L(n) asm volatile("s_waitcnt lgkmcnt(" #n ")" ::: "memory")
; #define PG8_BAR __builtin_amdgcn_s_barrier()
; #define PG8_SCHED __builtin_amdgcn_sched_barrier(0)
; template <class Epi, class Sched, bool ALIGN_EPI = false, bool SP2 = false>
; __device__ __forceinline__ void gemm_phase(PG8_LAS unsigned char* lds, const Gemm g, const Sched& S, const Epi& E) {
;     ...
;             PG8_WAIT_V(8); PG8_WAIT_L(0); PG8_BAR; PG8_MMA(1, 0, At, B0); PG8_MMA(1, 1, At, B1); PG8_BAR; PG8_SCHED;
;             PG8_LDB(B0, 1, 0); PG8_LDB(B1, 1, 1); PG8_SCHED; PG8_LDA(At, 1, 0); PG8_STAGE(PG8_SA(0, 1), a2 + hstep, voffA);
;             PG8_WAIT_V(8); PG8_WAIT_L(0); PG8_BAR; PG8_MMA(0, 0, At, B0); PG8_MMA(0, 1, At, B1); PG8_BAR; PG8_SCHED;
	v_mfma_f32_16x16x32_bf16 v[60:63], v[128:131], v[182:185], v[60:63]
	v_mfma_f32_16x16x32_bf16 v[56:59], v[136:139], v[182:185], v[56:59]
	v_mfma_f32_16x16x32_bf16 v[48:51], v[128:131], v[194:197], v[48:51]
	v_mfma_f32_16x16x32_bf16 v[40:43], v[136:139], v[194:197], v[40:43]
	v_mfma_f32_16x16x32_bf16 v[32:35], v[128:131], v[202:205], v[32:35]
	v_mfma_f32_16x16x32_bf16 v[24:27], v[136:139], v[202:205], v[24:27]
	v_mfma_f32_16x16x32_bf16 v[16:19], v[128:131], v[210:213], v[16:19]
	v_mfma_f32_16x16x32_bf16 v[8:11], v[136:139], v[210:213], v[8:11]
	v_mfma_f32_16x16x32_bf16 v[60:63], v[132:135], v[186:189], v[60:63]
	v_mfma_f32_16x16x32_bf16 v[56:59], v[140:143], v[186:189], v[56:59]
	v_mfma_f32_16x16x32_bf16 v[48:51], v[132:135], v[198:201], v[48:51]
	v_mfma_f32_16x16x32_bf16 v[40:43], v[140:143], v[198:201], v[40:43]
	v_mfma_f32_16x16x32_bf16 v[32:35], v[132:135], v[206:209], v[32:35]
	v_mfma_f32_16x16x32_bf16 v[24:27], v[140:143], v[206:209], v[24:27]
	v_mfma_f32_16x16x32_bf16 v[16:19], v[132:135], v[214:217], v[16:19]
	v_mfma_f32_16x16x32_bf16 v[8:11], v[140:143], v[214:217], v[8:11]
	v_mfma_f32_16x16x32_bf16 v[52:55], v[166:169], v[182:185], v[52:55]
	v_mfma_f32_16x16x32_bf16 v[44:47], v[174:177], v[182:185], v[44:47]
	v_mfma_f32_16x16x32_bf16 v[36:39], v[166:169], v[194:197], v[36:39]
	v_mfma_f32_16x16x32_bf16 v[28:31], v[174:177], v[194:197], v[28:31]
	v_mfma_f32_16x16x32_bf16 v[20:23], v[166:169], v[202:205], v[20:23]
	v_mfma_f32_16x16x32_bf16 v[12:15], v[174:177], v[202:205], v[12:15]
	v_mfma_f32_16x16x32_bf16 v[4:7], v[166:169], v[210:213], v[4:7]
	v_mfma_f32_16x16x32_bf16 v[0:3], v[174:177], v[210:213], v[0:3]
	v_mfma_f32_16x16x32_bf16 v[52:55], v[170:173], v[186:189], v[52:55]
	v_mfma_f32_16x16x32_bf16 v[44:47], v[178:181], v[186:189], v[44:47]
	v_mfma_f32_16x16x32_bf16 v[36:39], v[170:173], v[198:201], v[36:39]
	v_mfma_f32_16x16x32_bf16 v[28:31], v[178:181], v[198:201], v[28:31]
	v_mfma_f32_16x16x32_bf16 v[20:23], v[170:173], v[206:209], v[20:23]
	v_mfma_f32_16x16x32_bf16 v[12:15], v[178:181], v[206:209], v[12:15]
	v_mfma_f32_16x16x32_bf16 v[4:7], v[170:173], v[214:217], v[4:7]
	v_mfma_f32_16x16x32_bf16 v[0:3], v[178:181], v[214:217], v[0:3]
	s_barrier
	s_setprio 0
	s_add_i32 s10, 0, 0x18000
	s_add_i32 s11, 0, 0x1c000
	v_add_u32_e32 v140, s10, v163
	v_add_u32_e32 v162, s11, v163
	ds_read_b128 v[128:131], v140
	ds_read_b128 v[132:135], v140 offset:1024
	ds_read_b128 v[136:139], v140 offset:2048
	ds_read_b128 v[140:143], v140 offset:3072
	ds_read_b128 v[166:169], v162
	ds_read_b128 v[170:173], v162 offset:1024
	ds_read_b128 v[174:177], v162 offset:2048
	ds_read_b128 v[178:181], v162 offset:3072
	s_add_u32 s60, s60, 0x40000
	s_addc_u32 s61, s61, 0
	s_mov_b32 m0, s66
	v_lshl_add_u64 v[224:225], s[60:61], 0, v[144:145]
	ds_read_b128 v[182:185], v165 offset:32768
	ds_read_b128 v[186:189], v165 offset:33792
	ds_read_b128 v[194:197], v165 offset:34816
	ds_read_b128 v[198:201], v165 offset:35840
	ds_read_b128 v[202:205], v165 offset:36864
	ds_read_b128 v[206:209], v165 offset:37888
	ds_read_b128 v[210:213], v165 offset:38912
	ds_read_b128 v[214:217], v165 offset:39936
	global_load_lds_dwordx4 v[224:225], off
	v_lshl_add_u64 v[224:225], s[60:61], 0, v[148:149]
	s_mov_b32 m0, s67
	s_nop 0
	global_load_lds_dwordx4 v[224:225], off
	s_waitcnt vmcnt(8)
	s_waitcnt lgkmcnt(0)
	s_setprio 1
	s_barrier
	v_mfma_f32_16x16x32_bf16 v[124:127], v[128:131], v[182:185], v[124:127]
	v_mfma_f32_16x16x32_bf16 v[120:123], v[136:139], v[182:185], v[120:123]
	v_mfma_f32_16x16x32_bf16 v[112:115], v[128:131], v[194:197], v[112:115]
	v_mfma_f32_16x16x32_bf16 v[104:107], v[136:139], v[194:197], v[104:107]
	v_mfma_f32_16x16x32_bf16 v[96:99], v[128:131], v[202:205], v[96:99]
	v_mfma_f32_16x16x32_bf16 v[88:91], v[136:139], v[202:205], v[88:91]
	v_mfma_f32_16x16x32_bf16 v[80:83], v[128:131], v[210:213], v[80:83]
	v_mfma_f32_16x16x32_bf16 v[72:75], v[136:139], v[210:213], v[72:75]
	v_mfma_f32_16x16x32_bf16 v[124:127], v[132:135], v[186:189], v[124:127]
	v_mfma_f32_16x16x32_bf16 v[120:123], v[140:143], v[186:189], v[120:123]
	v_mfma_f32_16x16x32_bf16 v[112:115], v[132:135], v[198:201], v[112:115]
	v_mfma_f32_16x16x32_bf16 v[104:107], v[140:143], v[198:201], v[104:107]
	v_mfma_f32_16x16x32_bf16 v[96:99], v[132:135], v[206:209], v[96:99]
	v_mfma_f32_16x16x32_bf16 v[88:91], v[140:143], v[206:209], v[88:91]
	v_mfma_f32_16x16x32_bf16 v[80:83], v[132:135], v[214:217], v[80:83]
	v_mfma_f32_16x16x32_bf16 v[72:75], v[140:143], v[214:217], v[72:75]
	v_mfma_f32_16x16x32_bf16 v[116:119], v[166:169], v[182:185], v[116:119]
	v_mfma_f32_16x16x32_bf16 v[108:111], v[174:177], v[182:185], v[108:111]
	v_mfma_f32_16x16x32_bf16 v[100:103], v[166:169], v[194:197], v[100:103]
	v_mfma_f32_16x16x32_bf16 v[92:95], v[174:177], v[194:197], v[92:95]
	v_mfma_f32_16x16x32_bf16 v[84:87], v[166:169], v[202:205], v[84:87]
	v_mfma_f32_16x16x32_bf16 v[76:79], v[174:177], v[202:205], v[76:79]
	v_mfma_f32_16x16x32_bf16 v[68:71], v[166:169], v[210:213], v[68:71]
	v_mfma_f32_16x16x32_bf16 v[64:67], v[174:177], v[210:213], v[64:67]
	v_mfma_f32_16x16x32_bf16 v[116:119], v[170:173], v[186:189], v[116:119]
	v_mfma_f32_16x16x32_bf16 v[108:111], v[178:181], v[186:189], v[108:111]
	v_mfma_f32_16x16x32_bf16 v[100:103], v[170:173], v[198:201], v[100:103]
	v_mfma_f32_16x16x32_bf16 v[92:95], v[178:181], v[198:201], v[92:95]
	v_mfma_f32_16x16x32_bf16 v[84:87], v[170:173], v[206:209], v[84:87]
	v_mfma_f32_16x16x32_bf16 v[76:79], v[178:181], v[206:209], v[76:79]
	v_mfma_f32_16x16x32_bf16 v[68:71], v[170:173], v[214:217], v[68:71]
	v_mfma_f32_16x16x32_bf16 v[64:67], v[178:181], v[214:217], v[64:67]
	s_barrier
; #define PG8_STAGE(bufoff, gbase, voff) do { _Pragma("unroll") for (int _i = 0; _i < 2; ++_i) \
;         __builtin_amdgcn_global_load_lds((const unsigned*)((const char*)(gbase) + (voff)[_i]), (PG8_LAS unsigned*)(lds + (bufoff) + ldsw + _i * 8192), 16, 0, 0); } while (0)
; #define PG8_LDA(dst, b, h) do { _Pragma("unroll") for (int m = 0; m < 4; ++m) _Pragma("unroll") for (int k = 0; k < 2; ++k) dst[m][k] = *(const PG8_LAS bf16x8*)(lds + PG8_SA(b, h) + aoff + m * 2048 + k * 1024); } while (0)
; #define PG8_MMA(ai, bj, At, Bt) do { __builtin_amdgcn_s_setprio(1); _Pragma("unroll") for (int m = 0; m < 4; ++m) _Pragma("unroll") for (int n = 0; n < 2; ++n) _Pragma("unroll") for (int k = 0; k < 2; ++k) \
;         acc[ai][bj][m][n] = __builtin_amdgcn_mfma_f32_16x16x32_bf16(Bt[n][k], At[m][k], acc[ai][bj][m][n], 0, 0, 0); __builtin_amdgcn_s_setprio(0); } while (0)
; #define PG8_WAIT_V(n) asm volatile("s_waitcnt vmcnt(" #n ")" ::: "memory")
; #define PG8_WAIT_L(n) asm volatile("s_waitcnt lgkmcnt(" #n ")" ::: "memory")
; #define PG8_BAR __builtin_amdgcn_s_barrier()
; #define PG8_SCHED __builtin_amdgcn_sched_barrier(0)
; template <class Epi, class Sched, bool ALIGN_EPI = false, bool SP2 = false>
; __device__ __forceinline__ void gemm_phase(PG8_LAS unsigned char* lds, const Gemm g, const Sched& S, const Epi& E) {
;     ...
;         for (int t = 0; t < nt; t += 2) {
;             const bool last = (t == nt - 2);
;             const char* a1 = cA + (size_t)(t + 1) * kstep;
;     ...
;             PG8_LDA(At, 1, 1); PG8_STAGE(PG8_SB(1, 0), b3, voffB); PG8_STAGE(PG8_SB(1, 1), b3 + hstep, voffB); PG8_STAGE(PG8_SA(1, 0), a3, voffA);
;             PG8_WAIT_V(8); PG8_WAIT_L(0); PG8_BAR; PG8_MMA(1, 0, At, B0); PG8_MMA(1, 1, At, B1); PG8_BAR; PG8_SCHED;
	s_setprio 0
	s_add_i32 s10, s10, s63
	v_lshl_add_u64 v[190:191], v[190:191], 0, s[36:37]
	s_mov_b32 m0, s10
	ds_read_b128 v[182:185], v165 offset:49152
	ds_read_b128 v[186:189], v165 offset:50176
	ds_read_b128 v[194:197], v165 offset:51200
	ds_read_b128 v[198:201], v165 offset:52224
	ds_read_b128 v[202:205], v165 offset:53248
	ds_read_b128 v[206:209], v165 offset:54272
	ds_read_b128 v[210:213], v165 offset:55296
	ds_read_b128 v[214:217], v165 offset:56320
	global_load_lds_dwordx4 v[190:191], off
	s_add_i32 m0, s10, 0x2000
	s_add_u32 s58, s58, 0x40080
	v_lshl_add_u64 v[190:191], v[218:219], 0, s[36:37]
	s_addc_u32 s59, s59, 0
	s_add_i32 s10, s11, s63
	global_load_lds_dwordx4 v[190:191], off
	v_lshl_add_u64 v[190:191], s[58:59], 0, v[146:147]
	s_mov_b32 m0, s10
	s_nop 0
	global_load_lds_dwordx4 v[190:191], off
	v_lshl_add_u64 v[190:191], s[58:59], 0, v[150:151]
	s_add_i32 m0, s10, 0x2000
	s_nop 0
	global_load_lds_dwordx4 v[190:191], off
	v_lshl_add_u64 v[190:191], v[220:221], 0, s[36:37]
	s_mov_b32 m0, s70
	s_nop 0
	global_load_lds_dwordx4 v[190:191], off
	v_lshl_add_u64 v[190:191], v[222:223], 0, s[36:37]
	s_mov_b32 m0, s71
	s_nop 0
	global_load_lds_dwordx4 v[190:191], off
	s_waitcnt vmcnt(8)
	s_waitcnt lgkmcnt(0)
	s_setprio 1
	s_barrier
	v_mfma_f32_16x16x32_bf16 v[60:63], v[128:131], v[182:185], v[60:63]
	v_mfma_f32_16x16x32_bf16 v[56:59], v[136:139], v[182:185], v[56:59]
	v_mfma_f32_16x16x32_bf16 v[48:51], v[128:131], v[194:197], v[48:51]
	v_mfma_f32_16x16x32_bf16 v[40:43], v[136:139], v[194:197], v[40:43]
	v_mfma_f32_16x16x32_bf16 v[32:35], v[128:131], v[202:205], v[32:35]
	v_mfma_f32_16x16x32_bf16 v[24:27], v[136:139], v[202:205], v[24:27]
	v_mfma_f32_16x16x32_bf16 v[16:19], v[128:131], v[210:213], v[16:19]
	v_mfma_f32_16x16x32_bf16 v[8:11], v[136:139], v[210:213], v[8:11]
	v_mfma_f32_16x16x32_bf16 v[60:63], v[132:135], v[186:189], v[60:63]
	v_mfma_f32_16x16x32_bf16 v[56:59], v[140:143], v[186:189], v[56:59]
	v_mfma_f32_16x16x32_bf16 v[48:51], v[132:135], v[198:201], v[48:51]
	v_mfma_f32_16x16x32_bf16 v[40:43], v[140:143], v[198:201], v[40:43]
	v_mfma_f32_16x16x32_bf16 v[32:35], v[132:135], v[206:209], v[32:35]
	v_mfma_f32_16x16x32_bf16 v[24:27], v[140:143], v[206:209], v[24:27]
	v_mfma_f32_16x16x32_bf16 v[16:19], v[132:135], v[214:217], v[16:19]
	v_mfma_f32_16x16x32_bf16 v[8:11], v[140:143], v[214:217], v[8:11]
	v_mfma_f32_16x16x32_bf16 v[52:55], v[166:169], v[182:185], v[52:55]
	v_mfma_f32_16x16x32_bf16 v[44:47], v[174:177], v[182:185], v[44:47]
	v_mfma_f32_16x16x32_bf16 v[36:39], v[166:169], v[194:197], v[36:39]
	v_mfma_f32_16x16x32_bf16 v[28:31], v[174:177], v[194:197], v[28:31]
	v_mfma_f32_16x16x32_bf16 v[20:23], v[166:169], v[202:205], v[20:23]
	v_mfma_f32_16x16x32_bf16 v[12:15], v[174:177], v[202:205], v[12:15]
	v_mfma_f32_16x16x32_bf16 v[4:7], v[166:169], v[210:213], v[4:7]
	v_mfma_f32_16x16x32_bf16 v[0:3], v[174:177], v[210:213], v[0:3]
	v_mfma_f32_16x16x32_bf16 v[52:55], v[170:173], v[186:189], v[52:55]
	v_mfma_f32_16x16x32_bf16 v[44:47], v[178:181], v[186:189], v[44:47]
	v_mfma_f32_16x16x32_bf16 v[36:39], v[170:173], v[198:201], v[36:39]
	v_mfma_f32_16x16x32_bf16 v[28:31], v[178:181], v[198:201], v[28:31]
	v_mfma_f32_16x16x32_bf16 v[20:23], v[170:173], v[206:209], v[20:23]
	v_mfma_f32_16x16x32_bf16 v[12:15], v[178:181], v[206:209], v[12:15]
	v_mfma_f32_16x16x32_bf16 v[4:7], v[170:173], v[214:217], v[4:7]
	v_mfma_f32_16x16x32_bf16 v[0:3], v[178:181], v[214:217], v[0:3]
	s_barrier
	s_setprio 0
	s_add_i32 s76, s76, 2
	s_add_u32 s56, s56, 0x100
	s_addc_u32 s57, s57, 0
	s_add_u32 s49, s49, 0x100
	s_addc_u32 s51, s51, 0
	s_cmp_gt_u32 s76, 13
	s_cbranch_scc0 .LBB0_200
	s_and_b64 vcc, exec, s[44:45]
	s_cbranch_vccz .LBB0_203
	s_barrier

; #define PG8_STAGE(bufoff, gbase, voff) do { _Pragma("unroll") for (int _i = 0; _i < 2; ++_i) \
;         __builtin_amdgcn_global_load_lds((const unsigned*)((const char*)(gbase) + (voff)[_i]), (PG8_LAS unsigned*)(lds + (bufoff) + ldsw + _i * 8192), 16, 0, 0); } while (0)
; #define PG8_LDA(dst, b, h) do { _Pragma("unroll") for (int m = 0; m < 4; ++m) _Pragma("unroll") for (int k = 0; k < 2; ++k) dst[m][k] = *(const PG8_LAS bf16x8*)(lds + PG8_SA(b, h) + aoff + m * 2048 + k * 1024); } while (0)
; #define PG8_LDB(dst, b, h) do { _Pragma("unroll") for (int n = 0; n < 2; ++n) _Pragma("unroll") for (int k = 0; k < 2; ++k) dst[n][k] = *(const PG8_LAS bf16x8*)(lds + PG8_SB(b, h) + boff + n * 2048 + k * 1024); } while (0)
; #define PG8_MMA(ai, bj, At, Bt) do { __builtin_amdgcn_s_setprio(1); _Pragma("unroll") for (int m = 0; m < 4; ++m) _Pragma("unroll") for (int n = 0; n < 2; ++n) _Pragma("unroll") for (int k = 0; k < 2; ++k) \
;         acc[ai][bj][m][n] = __builtin_amdgcn_mfma_f32_16x16x32_bf16(Bt[n][k], At[m][k], acc[ai][bj][m][n], 0, 0, 0); __builtin_amdgcn_s_setprio(0); } while (0)
; #define PG8_WAIT_V(n) asm volatile("s_waitcnt vmcnt(" #n ")" ::: "memory")
; #define PG8_WAIT_L(n) asm volatile("s_waitcnt lgkmcnt(" #n ")" ::: "memory")
; template <class Epi, class Sched, bool ALIGN_EPI = false, bool SP2 = false>
; __device__ __forceinline__ void gemm_phase(PG8_LAS unsigned char* lds, const Gemm g, const Sched& S, const Epi& E) {
;     ...
;             const bool last = (t == nt - 2);
;             const char* a1 = cA + (size_t)(t + 1) * kstep;
;             const char* a2 = last ? nA : cA + (size_t)(t + 2) * kstep; const char* b2 = last ? nB : cB + (size_t)(t + 2) * kstep;
;             const char* a3 = a2 + kstep; const char* b3 = b2 + kstep;
;             if (last && has_next) S.a_ready(nxt);
;             if constexpr (SP2) {
;             PG8_LDB(B0, 0, 0); PG8_LDB(B1, 0, 1); PG8_SCHED; PG8_LDA(At, 0, 0); PG8_STAGE(PG8_SA(1, 1), a1 + hstep, voffA);
;             PG8_WAIT_V(8); PG8_WAIT_L(0); PG8_BAR; PG8_MMA(0, 0, At, B0); PG8_MMA(0, 1, At, B1); PG8_BAR; PG8_SCHED;
;             PG8_LDA(At, 0, 1); PG8_STAGE(PG8_SB(0, 0), b2, voffB); PG8_STAGE(PG8_SB(0, 1), b2 + hstep, voffB); PG8_STAGE(PG8_SA(0, 0), a2, voffA);
;             PG8_WAIT_V(8); PG8_WAIT_L(0); PG8_BAR; PG8_MMA(1, 0, At, B0); PG8_MMA(1, 1, At, B1); PG8_BAR; PG8_SCHED;
.LBB0_488:
	s_add_u32 s10, s34, 0xfffc0080
	s_addc_u32 s11, s35, -1
	s_add_i32 s77, 0, 0x10000
	s_cmp_eq_u32 s76, 4
	s_cselect_b32 s53, s45, s11
	s_cselect_b32 s52, s44, s10
	s_cselect_b32 s51, s49, s75
	s_cselect_b32 s50, s48, s19
	s_add_i32 s78, 0, 0x14000
	v_add_u32_e32 v140, s77, v246
	v_add_u32_e32 v156, s77, v246
	v_add_u32_e32 v156, 0x1000, v156
	ds_read_b128 v[128:131], v140
	ds_read_b128 v[132:135], v140 offset:1024
	ds_read_b128 v[136:139], v140 offset:2048
	ds_read_b128 v[140:143], v140 offset:3072
	ds_read_b128 v[144:147], v156
	ds_read_b128 v[148:151], v156 offset:1024
	ds_read_b128 v[152:155], v156 offset:2048
	ds_read_b128 v[156:159], v156 offset:3072
	v_lshl_add_u64 v[208:209], s[34:35], 0, v[204:205]
	s_add_i32 m0, s55, 0xc000
	ds_read_b128 v[160:163], v249
	ds_read_b128 v[164:167], v249 offset:1024
	ds_read_b128 v[168:171], v249 offset:2048
	ds_read_b128 v[172:175], v249 offset:3072
	ds_read_b128 v[176:179], v249 offset:4096
	ds_read_b128 v[180:183], v249 offset:5120
	ds_read_b128 v[184:187], v249 offset:6144
	ds_read_b128 v[188:191], v249 offset:7168
	global_load_lds_dwordx4 v[208:209], off
	v_lshl_add_u64 v[208:209], s[34:35], 0, v[206:207]
	s_add_i32 m0, s55, 0xe000
	s_nop 0
	global_load_lds_dwordx4 v[208:209], off
	s_waitcnt vmcnt(8)
	s_waitcnt lgkmcnt(0)
	s_setprio 1
	s_barrier
	v_mfma_f32_16x16x32_bf16 v[124:127], v[128:131], v[160:163], v[124:127]
	v_mfma_f32_16x16x32_bf16 v[120:123], v[136:139], v[160:163], v[120:123]
	v_mfma_f32_16x16x32_bf16 v[116:119], v[128:131], v[168:171], v[116:119]
	v_mfma_f32_16x16x32_bf16 v[112:115], v[136:139], v[168:171], v[112:115]
	v_mfma_f32_16x16x32_bf16 v[108:111], v[128:131], v[176:179], v[108:111]
	v_mfma_f32_16x16x32_bf16 v[104:107], v[136:139], v[176:179], v[104:107]
	v_mfma_f32_16x16x32_bf16 v[100:103], v[128:131], v[184:187], v[100:103]
	v_mfma_f32_16x16x32_bf16 v[96:99], v[136:139], v[184:187], v[96:99]
	v_mfma_f32_16x16x32_bf16 v[124:127], v[132:135], v[164:167], v[124:127]
	v_mfma_f32_16x16x32_bf16 v[120:123], v[140:143], v[164:167], v[120:123]
	v_mfma_f32_16x16x32_bf16 v[116:119], v[132:135], v[172:175], v[116:119]
	v_mfma_f32_16x16x32_bf16 v[112:115], v[140:143], v[172:175], v[112:115]
	v_mfma_f32_16x16x32_bf16 v[108:111], v[132:135], v[180:183], v[108:111]
	v_mfma_f32_16x16x32_bf16 v[104:107], v[140:143], v[180:183], v[104:107]
	v_mfma_f32_16x16x32_bf16 v[100:103], v[132:135], v[188:191], v[100:103]
	v_mfma_f32_16x16x32_bf16 v[96:99], v[140:143], v[188:191], v[96:99]
	v_mfma_f32_16x16x32_bf16 v[92:95], v[144:147], v[160:163], v[92:95]
	v_mfma_f32_16x16x32_bf16 v[88:91], v[152:155], v[160:163], v[88:91]
	v_mfma_f32_16x16x32_bf16 v[84:87], v[144:147], v[168:171], v[84:87]
	v_mfma_f32_16x16x32_bf16 v[80:83], v[152:155], v[168:171], v[80:83]
	v_mfma_f32_16x16x32_bf16 v[76:79], v[144:147], v[176:179], v[76:79]
	v_mfma_f32_16x16x32_bf16 v[72:75], v[152:155], v[176:179], v[72:75]
	v_mfma_f32_16x16x32_bf16 v[68:71], v[144:147], v[184:187], v[68:71]
	v_mfma_f32_16x16x32_bf16 v[64:67], v[152:155], v[184:187], v[64:67]
	v_mfma_f32_16x16x32_bf16 v[92:95], v[148:151], v[164:167], v[92:95]
	v_mfma_f32_16x16x32_bf16 v[88:91], v[156:159], v[164:167], v[88:91]
	v_mfma_f32_16x16x32_bf16 v[84:87], v[148:151], v[172:175], v[84:87]
	v_mfma_f32_16x16x32_bf16 v[80:83], v[156:159], v[172:175], v[80:83]
	v_mfma_f32_16x16x32_bf16 v[76:79], v[148:151], v[180:183], v[76:79]
	v_mfma_f32_16x16x32_bf16 v[72:75], v[156:159], v[180:183], v[72:75]
	v_mfma_f32_16x16x32_bf16 v[68:71], v[148:151], v[188:191], v[68:71]
	v_mfma_f32_16x16x32_bf16 v[64:67], v[156:159], v[188:191], v[64:67]
	s_barrier
	s_setprio 0
	s_add_i32 s10, s77, s14
	v_lshl_add_u64 v[208:209], s[50:51], 0, v[198:199]
	s_mov_b32 m0, s10
	ds_read_b128 v[160:163], v249 offset:16384
	ds_read_b128 v[164:167], v249 offset:17408
	ds_read_b128 v[168:171], v249 offset:18432
	ds_read_b128 v[172:175], v249 offset:19456
	ds_read_b128 v[176:179], v249 offset:20480
	ds_read_b128 v[180:183], v249 offset:21504
	ds_read_b128 v[184:187], v249 offset:22528
	ds_read_b128 v[188:191], v249 offset:23552
	global_load_lds_dwordx4 v[208:209], off
	s_add_i32 m0, s10, 0x2000
	s_add_u32 s10, s50, 0x40000
	v_lshl_add_u64 v[210:211], s[50:51], 0, v[194:195]
	s_addc_u32 s11, s51, 0
	s_add_i32 s77, s78, s14
	global_load_lds_dwordx4 v[210:211], off
	v_lshl_add_u64 v[212:213], s[10:11], 0, v[198:199]
	s_mov_b32 m0, s77
	v_lshl_add_u64 v[214:215], s[52:53], 0, v[196:197]
	global_load_lds_dwordx4 v[212:213], off
	v_lshl_add_u64 v[212:213], s[10:11], 0, v[194:195]
	s_add_i32 m0, s77, 0x2000
	s_nop 0
	global_load_lds_dwordx4 v[212:213], off
	v_lshl_add_u64 v[212:213], s[52:53], 0, v[200:201]
	s_mov_b32 m0, s55
	s_nop 0
	global_load_lds_dwordx4 v[212:213], off
	s_mov_b32 m0, s58
	s_nop 0
	global_load_lds_dwordx4 v[214:215], off
	s_waitcnt vmcnt(8)
	s_waitcnt lgkmcnt(0)
	s_setprio 1
	s_barrier
; #define PG8_STAGE(bufoff, gbase, voff) do { _Pragma("unroll") for (int _i = 0; _i < 2; ++_i) \
;         __builtin_amdgcn_global_load_lds((const unsigned*)((const char*)(gbase) + (voff)[_i]), (PG8_LAS unsigned*)(lds + (bufoff) + ldsw + _i * 8192), 16, 0, 0); } while (0)
; #define PG8_LDA(dst, b, h) do { _Pragma("unroll") for (int m = 0; m < 4; ++m) _Pragma("unroll") for (int k = 0; k < 2; ++k) dst[m][k] = *(const PG8_LAS bf16x8*)(lds + PG8_SA(b, h) + aoff + m * 2048 + k * 1024); } while (0)
; #define PG8_LDB(dst, b, h) do { _Pragma("unroll") for (int n = 0; n < 2; ++n) _Pragma("unroll") for (int k = 0; k < 2; ++k) dst[n][k] = *(const PG8_LAS bf16x8*)(lds + PG8_SB(b, h) + boff + n * 2048 + k * 1024); } while (0)
; #define PG8_MMA(ai, bj, At, Bt) do { __builtin_amdgcn_s_setprio(1); _Pragma("unroll") for (int m = 0; m < 4; ++m) _Pragma("unroll") for (int n = 0; n < 2; ++n) _Pragma("unroll") for (int k = 0; k < 2; ++k) \
;         acc[ai][bj][m][n] = __builtin_amdgcn_mfma_f32_16x16x32_bf16(Bt[n][k], At[m][k], acc[ai][bj][m][n], 0, 0, 0); __builtin_amdgcn_s_setprio(0); } while (0)
; #define PG8_WAIT_V(n) asm volatile("s_waitcnt vmcnt(" #n ")" ::: "memory")
; #define PG8_WAIT_L(n) asm volatile("s_waitcnt lgkmcnt(" #n ")" ::: "memory")
; #define PG8_BAR __builtin_amdgcn_s_barrier()
; #define PG8_SCHED __builtin_amdgcn_sched_barrier(0)
; template <class Epi, class Sched, bool ALIGN_EPI = false, bool SP2 = false>
; __device__ __forceinline__ void gemm_phase(PG8_LAS unsigned char* lds, const Gemm g, const Sched& S, const Epi& E) {
;     ...
;             PG8_WAIT_V(8); PG8_WAIT_L(0); PG8_BAR; PG8_MMA(1, 0, At, B0); PG8_MMA(1, 1, At, B1); PG8_BAR; PG8_SCHED;
;             PG8_LDB(B0, 1, 0); PG8_LDB(B1, 1, 1); PG8_SCHED; PG8_LDA(At, 1, 0); PG8_STAGE(PG8_SA(0, 1), a2 + hstep, voffA);
;             PG8_WAIT_V(8); PG8_WAIT_L(0); PG8_BAR; PG8_MMA(0, 0, At, B0); PG8_MMA(0, 1, At, B1); PG8_BAR; PG8_SCHED;
	v_mfma_f32_16x16x32_bf16 v[60:63], v[128:131], v[160:163], v[60:63]
	v_mfma_f32_16x16x32_bf16 v[56:59], v[136:139], v[160:163], v[56:59]
	v_mfma_f32_16x16x32_bf16 v[52:55], v[128:131], v[168:171], v[52:55]
	v_mfma_f32_16x16x32_bf16 v[48:51], v[136:139], v[168:171], v[48:51]
	v_mfma_f32_16x16x32_bf16 v[44:47], v[128:131], v[176:179], v[44:47]
	v_mfma_f32_16x16x32_bf16 v[40:43], v[136:139], v[176:179], v[40:43]
	v_mfma_f32_16x16x32_bf16 v[36:39], v[128:131], v[184:187], v[36:39]
	v_mfma_f32_16x16x32_bf16 v[32:35], v[136:139], v[184:187], v[32:35]
	v_mfma_f32_16x16x32_bf16 v[60:63], v[132:135], v[164:167], v[60:63]
	v_mfma_f32_16x16x32_bf16 v[56:59], v[140:143], v[164:167], v[56:59]
	v_mfma_f32_16x16x32_bf16 v[52:55], v[132:135], v[172:175], v[52:55]
	v_mfma_f32_16x16x32_bf16 v[48:51], v[140:143], v[172:175], v[48:51]
	v_mfma_f32_16x16x32_bf16 v[44:47], v[132:135], v[180:183], v[44:47]
	v_mfma_f32_16x16x32_bf16 v[40:43], v[140:143], v[180:183], v[40:43]
	v_mfma_f32_16x16x32_bf16 v[36:39], v[132:135], v[188:191], v[36:39]
	v_mfma_f32_16x16x32_bf16 v[32:35], v[140:143], v[188:191], v[32:35]
	v_mfma_f32_16x16x32_bf16 v[28:31], v[144:147], v[160:163], v[28:31]
	v_mfma_f32_16x16x32_bf16 v[24:27], v[152:155], v[160:163], v[24:27]
	v_mfma_f32_16x16x32_bf16 v[20:23], v[144:147], v[168:171], v[20:23]
	v_mfma_f32_16x16x32_bf16 v[16:19], v[152:155], v[168:171], v[16:19]
	v_mfma_f32_16x16x32_bf16 v[12:15], v[144:147], v[176:179], v[12:15]
	v_mfma_f32_16x16x32_bf16 v[8:11], v[152:155], v[176:179], v[8:11]
	v_mfma_f32_16x16x32_bf16 v[4:7], v[144:147], v[184:187], v[4:7]
	v_mfma_f32_16x16x32_bf16 v[0:3], v[152:155], v[184:187], v[0:3]
	v_mfma_f32_16x16x32_bf16 v[28:31], v[148:151], v[164:167], v[28:31]
	v_mfma_f32_16x16x32_bf16 v[24:27], v[156:159], v[164:167], v[24:27]
	v_mfma_f32_16x16x32_bf16 v[20:23], v[148:151], v[172:175], v[20:23]
	v_mfma_f32_16x16x32_bf16 v[16:19], v[156:159], v[172:175], v[16:19]
	v_mfma_f32_16x16x32_bf16 v[12:15], v[148:151], v[180:183], v[12:15]
	v_mfma_f32_16x16x32_bf16 v[8:11], v[156:159], v[180:183], v[8:11]
	v_mfma_f32_16x16x32_bf16 v[4:7], v[148:151], v[188:191], v[4:7]
	v_mfma_f32_16x16x32_bf16 v[0:3], v[156:159], v[188:191], v[0:3]
	s_barrier
	s_setprio 0
	s_add_i32 s77, 0, 0x18000
	s_add_i32 s78, 0, 0x1c000
	v_add_u32_e32 v140, s77, v246
	v_add_u32_e32 v156, s77, v246
	v_add_u32_e32 v156, 0x1000, v156
	ds_read_b128 v[128:131], v140
	ds_read_b128 v[132:135], v140 offset:1024
	ds_read_b128 v[136:139], v140 offset:2048
	ds_read_b128 v[140:143], v140 offset:3072
	ds_read_b128 v[144:147], v156
	ds_read_b128 v[148:151], v156 offset:1024
	ds_read_b128 v[152:155], v156 offset:2048
	ds_read_b128 v[156:159], v156 offset:3072
	s_add_u32 s10, s52, 0x40000
	s_addc_u32 s11, s53, 0
	s_mov_b32 m0, s59
	v_lshl_add_u64 v[216:217], s[10:11], 0, v[200:201]
	ds_read_b128 v[160:163], v249 offset:32768
	ds_read_b128 v[164:167], v249 offset:33792
	ds_read_b128 v[168:171], v249 offset:34816
	ds_read_b128 v[172:175], v249 offset:35840
	ds_read_b128 v[176:179], v249 offset:36864
	ds_read_b128 v[180:183], v249 offset:37888
	ds_read_b128 v[184:187], v249 offset:38912
	ds_read_b128 v[188:191], v249 offset:39936
	global_load_lds_dwordx4 v[216:217], off
	v_lshl_add_u64 v[216:217], s[10:11], 0, v[196:197]
	s_mov_b32 m0, s60
	s_nop 0
	global_load_lds_dwordx4 v[216:217], off
	s_waitcnt vmcnt(8)
	s_waitcnt lgkmcnt(0)
	s_setprio 1
	s_barrier
	v_mfma_f32_16x16x32_bf16 v[124:127], v[128:131], v[160:163], v[124:127]
	v_mfma_f32_16x16x32_bf16 v[120:123], v[136:139], v[160:163], v[120:123]
	v_mfma_f32_16x16x32_bf16 v[116:119], v[128:131], v[168:171], v[116:119]
	v_mfma_f32_16x16x32_bf16 v[112:115], v[136:139], v[168:171], v[112:115]
	v_mfma_f32_16x16x32_bf16 v[108:111], v[128:131], v[176:179], v[108:111]
	v_mfma_f32_16x16x32_bf16 v[104:107], v[136:139], v[176:179], v[104:107]
	v_mfma_f32_16x16x32_bf16 v[100:103], v[128:131], v[184:187], v[100:103]
	v_mfma_f32_16x16x32_bf16 v[96:99], v[136:139], v[184:187], v[96:99]
	v_mfma_f32_16x16x32_bf16 v[124:127], v[132:135], v[164:167], v[124:127]
	v_mfma_f32_16x16x32_bf16 v[120:123], v[140:143], v[164:167], v[120:123]
	v_mfma_f32_16x16x32_bf16 v[116:119], v[132:135], v[172:175], v[116:119]
	v_mfma_f32_16x16x32_bf16 v[112:115], v[140:143], v[172:175], v[112:115]
	v_mfma_f32_16x16x32_bf16 v[108:111], v[132:135], v[180:183], v[108:111]
	v_mfma_f32_16x16x32_bf16 v[104:107], v[140:143], v[180:183], v[104:107]
	v_mfma_f32_16x16x32_bf16 v[100:103], v[132:135], v[188:191], v[100:103]
	v_mfma_f32_16x16x32_bf16 v[96:99], v[140:143], v[188:191], v[96:99]
	v_mfma_f32_16x16x32_bf16 v[92:95], v[144:147], v[160:163], v[92:95]
	v_mfma_f32_16x16x32_bf16 v[88:91], v[152:155], v[160:163], v[88:91]
	v_mfma_f32_16x16x32_bf16 v[84:87], v[144:147], v[168:171], v[84:87]
	v_mfma_f32_16x16x32_bf16 v[80:83], v[152:155], v[168:171], v[80:83]
	v_mfma_f32_16x16x32_bf16 v[76:79], v[144:147], v[176:179], v[76:79]
	v_mfma_f32_16x16x32_bf16 v[72:75], v[152:155], v[176:179], v[72:75]
	v_mfma_f32_16x16x32_bf16 v[68:71], v[144:147], v[184:187], v[68:71]
	v_mfma_f32_16x16x32_bf16 v[64:67], v[152:155], v[184:187], v[64:67]
	v_mfma_f32_16x16x32_bf16 v[92:95], v[148:151], v[164:167], v[92:95]
	v_mfma_f32_16x16x32_bf16 v[88:91], v[156:159], v[164:167], v[88:91]
	v_mfma_f32_16x16x32_bf16 v[84:87], v[148:151], v[172:175], v[84:87]
	v_mfma_f32_16x16x32_bf16 v[80:83], v[156:159], v[172:175], v[80:83]
	v_mfma_f32_16x16x32_bf16 v[76:79], v[148:151], v[180:183], v[76:79]
	v_mfma_f32_16x16x32_bf16 v[72:75], v[156:159], v[180:183], v[72:75]
	v_mfma_f32_16x16x32_bf16 v[68:71], v[148:151], v[188:191], v[68:71]
	v_mfma_f32_16x16x32_bf16 v[64:67], v[156:159], v[188:191], v[64:67]
	s_barrier
; #define PG8_STAGE(bufoff, gbase, voff) do { _Pragma("unroll") for (int _i = 0; _i < 2; ++_i) \
;         __builtin_amdgcn_global_load_lds((const unsigned*)((const char*)(gbase) + (voff)[_i]), (PG8_LAS unsigned*)(lds + (bufoff) + ldsw + _i * 8192), 16, 0, 0); } while (0)
; #define PG8_LDA(dst, b, h) do { _Pragma("unroll") for (int m = 0; m < 4; ++m) _Pragma("unroll") for (int k = 0; k < 2; ++k) dst[m][k] = *(const PG8_LAS bf16x8*)(lds + PG8_SA(b, h) + aoff + m * 2048 + k * 1024); } while (0)
; #define PG8_MMA(ai, bj, At, Bt) do { __builtin_amdgcn_s_setprio(1); _Pragma("unroll") for (int m = 0; m < 4; ++m) _Pragma("unroll") for (int n = 0; n < 2; ++n) _Pragma("unroll") for (int k = 0; k < 2; ++k) \
;         acc[ai][bj][m][n] = __builtin_amdgcn_mfma_f32_16x16x32_bf16(Bt[n][k], At[m][k], acc[ai][bj][m][n], 0, 0, 0); __builtin_amdgcn_s_setprio(0); } while (0)
; #define PG8_WAIT_V(n) asm volatile("s_waitcnt vmcnt(" #n ")" ::: "memory")
; #define PG8_WAIT_L(n) asm volatile("s_waitcnt lgkmcnt(" #n ")" ::: "memory")
; #define PG8_BAR __builtin_amdgcn_s_barrier()
; #define PG8_SCHED __builtin_amdgcn_sched_barrier(0)
; template <class Epi, class Sched, bool ALIGN_EPI = false, bool SP2 = false>
; __device__ __forceinline__ void gemm_phase(PG8_LAS unsigned char* lds, const Gemm g, const Sched& S, const Epi& E) {
;     ...
;         for (int t = 0; t < nt; t += 2) {
;             const bool last = (t == nt - 2);
;             const char* a1 = cA + (size_t)(t + 1) * kstep;
;     ...
;             PG8_LDA(At, 1, 1); PG8_STAGE(PG8_SB(1, 0), b3, voffB); PG8_STAGE(PG8_SB(1, 1), b3 + hstep, voffB); PG8_STAGE(PG8_SA(1, 0), a3, voffA);
;             PG8_WAIT_V(8); PG8_WAIT_L(0); PG8_BAR; PG8_MMA(1, 0, At, B0); PG8_MMA(1, 1, At, B1); PG8_BAR; PG8_SCHED;
	s_setprio 0
	s_add_i32 s10, s77, s14
	v_lshl_add_u64 v[208:209], v[208:209], 0, s[36:37]
	s_mov_b32 m0, s10
	ds_read_b128 v[160:163], v249 offset:49152
	ds_read_b128 v[164:167], v249 offset:50176
	ds_read_b128 v[168:171], v249 offset:51200
	ds_read_b128 v[172:175], v249 offset:52224
	ds_read_b128 v[176:179], v249 offset:53248
	ds_read_b128 v[180:183], v249 offset:54272
	ds_read_b128 v[184:187], v249 offset:55296
	ds_read_b128 v[188:191], v249 offset:56320
	global_load_lds_dwordx4 v[208:209], off
	s_add_i32 m0, s10, 0x2000
	s_add_u32 s10, s50, 0x40080
	v_lshl_add_u64 v[208:209], v[210:211], 0, s[36:37]
	s_addc_u32 s11, s51, 0
	s_add_i32 s50, s78, s14
	global_load_lds_dwordx4 v[208:209], off
	v_lshl_add_u64 v[208:209], s[10:11], 0, v[198:199]
	s_mov_b32 m0, s50
	s_nop 0
	global_load_lds_dwordx4 v[208:209], off
	v_lshl_add_u64 v[208:209], s[10:11], 0, v[194:195]
	s_add_i32 m0, s50, 0x2000
	s_nop 0
	global_load_lds_dwordx4 v[208:209], off
	v_lshl_add_u64 v[208:209], v[212:213], 0, s[36:37]
	s_mov_b32 m0, s65
	s_nop 0
	global_load_lds_dwordx4 v[208:209], off
	v_lshl_add_u64 v[208:209], v[214:215], 0, s[36:37]
	s_mov_b32 m0, s66
	s_nop 0
	global_load_lds_dwordx4 v[208:209], off
	s_waitcnt vmcnt(8)
	s_waitcnt lgkmcnt(0)
	s_setprio 1
	s_barrier
	v_mfma_f32_16x16x32_bf16 v[60:63], v[128:131], v[160:163], v[60:63]
	v_mfma_f32_16x16x32_bf16 v[56:59], v[136:139], v[160:163], v[56:59]
	v_mfma_f32_16x16x32_bf16 v[52:55], v[128:131], v[168:171], v[52:55]
	v_mfma_f32_16x16x32_bf16 v[48:51], v[136:139], v[168:171], v[48:51]
	v_mfma_f32_16x16x32_bf16 v[44:47], v[128:131], v[176:179], v[44:47]
	v_mfma_f32_16x16x32_bf16 v[40:43], v[136:139], v[176:179], v[40:43]
	v_mfma_f32_16x16x32_bf16 v[36:39], v[128:131], v[184:187], v[36:39]
	v_mfma_f32_16x16x32_bf16 v[32:35], v[136:139], v[184:187], v[32:35]
	v_mfma_f32_16x16x32_bf16 v[60:63], v[132:135], v[164:167], v[60:63]
	v_mfma_f32_16x16x32_bf16 v[56:59], v[140:143], v[164:167], v[56:59]
	v_mfma_f32_16x16x32_bf16 v[52:55], v[132:135], v[172:175], v[52:55]
	v_mfma_f32_16x16x32_bf16 v[48:51], v[140:143], v[172:175], v[48:51]
	v_mfma_f32_16x16x32_bf16 v[44:47], v[132:135], v[180:183], v[44:47]
	v_mfma_f32_16x16x32_bf16 v[40:43], v[140:143], v[180:183], v[40:43]
	v_mfma_f32_16x16x32_bf16 v[36:39], v[132:135], v[188:191], v[36:39]
	v_mfma_f32_16x16x32_bf16 v[32:35], v[140:143], v[188:191], v[32:35]
	v_mfma_f32_16x16x32_bf16 v[28:31], v[144:147], v[160:163], v[28:31]
	v_mfma_f32_16x16x32_bf16 v[24:27], v[152:155], v[160:163], v[24:27]
	v_mfma_f32_16x16x32_bf16 v[20:23], v[144:147], v[168:171], v[20:23]
	v_mfma_f32_16x16x32_bf16 v[16:19], v[152:155], v[168:171], v[16:19]
	v_mfma_f32_16x16x32_bf16 v[12:15], v[144:147], v[176:179], v[12:15]
	v_mfma_f32_16x16x32_bf16 v[8:11], v[152:155], v[176:179], v[8:11]
	v_mfma_f32_16x16x32_bf16 v[4:7], v[144:147], v[184:187], v[4:7]
	v_mfma_f32_16x16x32_bf16 v[0:3], v[152:155], v[184:187], v[0:3]
	v_mfma_f32_16x16x32_bf16 v[28:31], v[148:151], v[164:167], v[28:31]
	v_mfma_f32_16x16x32_bf16 v[24:27], v[156:159], v[164:167], v[24:27]
	v_mfma_f32_16x16x32_bf16 v[20:23], v[148:151], v[172:175], v[20:23]
	v_mfma_f32_16x16x32_bf16 v[16:19], v[156:159], v[172:175], v[16:19]
	v_mfma_f32_16x16x32_bf16 v[12:15], v[148:151], v[180:183], v[12:15]
	v_mfma_f32_16x16x32_bf16 v[8:11], v[156:159], v[180:183], v[8:11]
	v_mfma_f32_16x16x32_bf16 v[4:7], v[148:151], v[188:191], v[4:7]
	v_mfma_f32_16x16x32_bf16 v[0:3], v[156:159], v[188:191], v[0:3]
	s_barrier
	s_setprio 0
	s_add_i32 s76, s76, 2
	s_add_u32 s34, s34, 0x100
	s_addc_u32 s35, s35, 0
	s_add_u32 s19, s19, 0x100
	s_addc_u32 s75, s75, 0
	s_cmp_gt_u32 s76, 5
	s_cbranch_scc0 .LBB0_488
	s_and_b64 vcc, exec, s[24:25]
	s_cbranch_vccz .LBB0_491
	s_barrier

; #define PG8_STAGE(bufoff, gbase, voff) do { _Pragma("unroll") for (int _i = 0; _i < 2; ++_i) \
;         __builtin_amdgcn_global_load_lds((const unsigned*)((const char*)(gbase) + (voff)[_i]), (PG8_LAS unsigned*)(lds + (bufoff) + ldsw + _i * 8192), 16, 0, 0); } while (0)
; #define PG8_LDA(dst, b, h) do { _Pragma("unroll") for (int m = 0; m < 4; ++m) _Pragma("unroll") for (int k = 0; k < 2; ++k) dst[m][k] = *(const PG8_LAS bf16x8*)(lds + PG8_SA(b, h) + aoff + m * 2048 + k * 1024); } while (0)
; #define PG8_LDB(dst, b, h) do { _Pragma("unroll") for (int n = 0; n < 2; ++n) _Pragma("unroll") for (int k = 0; k < 2; ++k) dst[n][k] = *(const PG8_LAS bf16x8*)(lds + PG8_SB(b, h) + boff + n * 2048 + k * 1024); } while (0)
; #define PG8_MMA(ai, bj, At, Bt) do { __builtin_amdgcn_s_setprio(1); _Pragma("unroll") for (int m = 0; m < 4; ++m) _Pragma("unroll") for (int n = 0; n < 2; ++n) _Pragma("unroll") for (int k = 0; k < 2; ++k) \
;         acc[ai][bj][m][n] = __builtin_amdgcn_mfma_f32_16x16x32_bf16(Bt[n][k], At[m][k], acc[ai][bj][m][n], 0, 0, 0); __builtin_amdgcn_s_setprio(0); } while (0)
; #define PG8_WAIT_V(n) asm volatile("s_waitcnt vmcnt(" #n ")" ::: "memory")
; #define PG8_WAIT_L(n) asm volatile("s_waitcnt lgkmcnt(" #n ")" ::: "memory")
; template <class Epi, class Sched, bool ALIGN_EPI = false, bool SP2 = false>
; __device__ __forceinline__ void gemm_phase(PG8_LAS unsigned char* lds, const Gemm g, const Sched& S, const Epi& E) {
;     ...
;             const bool last = (t == nt - 2);
;             const char* a1 = cA + (size_t)(t + 1) * kstep;
;             const char* a2 = last ? nA : cA + (size_t)(t + 2) * kstep; const char* b2 = last ? nB : cB + (size_t)(t + 2) * kstep;
;             const char* a3 = a2 + kstep; const char* b3 = b2 + kstep;
;             if (last && has_next) S.a_ready(nxt);
;             if constexpr (SP2) {
;             PG8_LDB(B0, 0, 0); PG8_LDB(B1, 0, 1); PG8_SCHED; PG8_LDA(At, 0, 0); PG8_STAGE(PG8_SA(1, 1), a1 + hstep, voffA);
;             PG8_WAIT_V(8); PG8_WAIT_L(0); PG8_BAR; PG8_MMA(0, 0, At, B0); PG8_MMA(0, 1, At, B1); PG8_BAR; PG8_SCHED;
;             PG8_LDA(At, 0, 1); PG8_STAGE(PG8_SB(0, 0), b2, voffB); PG8_STAGE(PG8_SB(0, 1), b2 + hstep, voffB); PG8_STAGE(PG8_SA(0, 0), a2, voffA);
;             PG8_WAIT_V(8); PG8_WAIT_L(0); PG8_BAR; PG8_MMA(1, 0, At, B0); PG8_MMA(1, 1, At, B1); PG8_BAR; PG8_SCHED;
.LBB0_577:
	s_add_u32 s10, s44, 0xfffc0080
	s_addc_u32 s11, s45, -1
	s_add_i32 s64, 0, 0x10000
	s_cmp_eq_u32 s63, 12
	s_cselect_b32 s49, s29, s11
	s_cselect_b32 s48, s43, s10
	v_add_u32_e32 v146, s64, v149
	s_cselect_b32 s47, s27, s62
	s_cselect_b32 s46, s60, s61
	s_add_i32 s65, 0, 0x14000
	ds_read_b128 v[128:131], v146
	ds_read_b128 v[154:157], v146 offset:1024
	ds_read_b128 v[158:161], v146 offset:2048
	ds_read_b128 v[162:165], v146 offset:3072
	v_add_u32_e32 v146, s65, v149
	ds_read_b128 v[166:169], v146
	ds_read_b128 v[170:173], v146 offset:1024
	ds_read_b128 v[174:177], v146 offset:2048
	ds_read_b128 v[178:181], v146 offset:3072
	v_lshl_add_u64 v[190:191], s[44:45], 0, v[142:143]
	s_add_i32 m0, s51, 0xc000
	ds_read_b128 v[182:185], v153
	ds_read_b128 v[186:189], v153 offset:1024
	ds_read_b128 v[194:197], v153 offset:2048
	ds_read_b128 v[198:201], v153 offset:3072
	ds_read_b128 v[202:205], v153 offset:4096
	ds_read_b128 v[206:209], v153 offset:5120
	ds_read_b128 v[210:213], v153 offset:6144
	ds_read_b128 v[214:217], v153 offset:7168
	global_load_lds_dwordx4 v[190:191], off
	v_lshl_add_u64 v[190:191], s[44:45], 0, v[144:145]
	s_add_i32 m0, s51, 0xe000
	s_nop 0
	global_load_lds_dwordx4 v[190:191], off
	s_waitcnt vmcnt(8)
	s_waitcnt lgkmcnt(0)
	s_setprio 1
	s_barrier
	v_mfma_f32_16x16x32_bf16 v[124:127], v[128:131], v[182:185], v[124:127]
	v_mfma_f32_16x16x32_bf16 v[116:119], v[158:161], v[182:185], v[116:119]
	v_mfma_f32_16x16x32_bf16 v[108:111], v[128:131], v[194:197], v[108:111]
	v_mfma_f32_16x16x32_bf16 v[100:103], v[158:161], v[194:197], v[100:103]
	v_mfma_f32_16x16x32_bf16 v[92:95], v[128:131], v[202:205], v[92:95]
	v_mfma_f32_16x16x32_bf16 v[84:87], v[158:161], v[202:205], v[84:87]
	v_mfma_f32_16x16x32_bf16 v[76:79], v[128:131], v[210:213], v[76:79]
	v_mfma_f32_16x16x32_bf16 v[68:71], v[158:161], v[210:213], v[68:71]
	v_mfma_f32_16x16x32_bf16 v[124:127], v[154:157], v[186:189], v[124:127]
	v_mfma_f32_16x16x32_bf16 v[116:119], v[162:165], v[186:189], v[116:119]
	v_mfma_f32_16x16x32_bf16 v[108:111], v[154:157], v[198:201], v[108:111]
	v_mfma_f32_16x16x32_bf16 v[100:103], v[162:165], v[198:201], v[100:103]
	v_mfma_f32_16x16x32_bf16 v[92:95], v[154:157], v[206:209], v[92:95]
	v_mfma_f32_16x16x32_bf16 v[84:87], v[162:165], v[206:209], v[84:87]
	v_mfma_f32_16x16x32_bf16 v[76:79], v[154:157], v[214:217], v[76:79]
	v_mfma_f32_16x16x32_bf16 v[68:71], v[162:165], v[214:217], v[68:71]
	v_mfma_f32_16x16x32_bf16 v[120:123], v[166:169], v[182:185], v[120:123]
	v_mfma_f32_16x16x32_bf16 v[112:115], v[174:177], v[182:185], v[112:115]
	v_mfma_f32_16x16x32_bf16 v[104:107], v[166:169], v[194:197], v[104:107]
	v_mfma_f32_16x16x32_bf16 v[96:99], v[174:177], v[194:197], v[96:99]
	v_mfma_f32_16x16x32_bf16 v[88:91], v[166:169], v[202:205], v[88:91]
	v_mfma_f32_16x16x32_bf16 v[80:83], v[174:177], v[202:205], v[80:83]
	v_mfma_f32_16x16x32_bf16 v[72:75], v[166:169], v[210:213], v[72:75]
	v_mfma_f32_16x16x32_bf16 v[64:67], v[174:177], v[210:213], v[64:67]
	v_mfma_f32_16x16x32_bf16 v[120:123], v[170:173], v[186:189], v[120:123]
	v_mfma_f32_16x16x32_bf16 v[112:115], v[178:181], v[186:189], v[112:115]
	v_mfma_f32_16x16x32_bf16 v[104:107], v[170:173], v[198:201], v[104:107]
	v_mfma_f32_16x16x32_bf16 v[96:99], v[178:181], v[198:201], v[96:99]
	v_mfma_f32_16x16x32_bf16 v[88:91], v[170:173], v[206:209], v[88:91]
	v_mfma_f32_16x16x32_bf16 v[80:83], v[178:181], v[206:209], v[80:83]
	v_mfma_f32_16x16x32_bf16 v[72:75], v[170:173], v[214:217], v[72:75]
	v_mfma_f32_16x16x32_bf16 v[64:67], v[178:181], v[214:217], v[64:67]
	s_barrier
	s_setprio 0
	s_add_i32 s10, s64, s19
	v_lshl_add_u64 v[190:191], s[46:47], 0, v[136:137]
	s_mov_b32 m0, s10
	ds_read_b128 v[182:185], v153 offset:16384
	ds_read_b128 v[186:189], v153 offset:17408
	ds_read_b128 v[194:197], v153 offset:18432
	ds_read_b128 v[198:201], v153 offset:19456
	ds_read_b128 v[202:205], v153 offset:20480
	ds_read_b128 v[206:209], v153 offset:21504
	ds_read_b128 v[210:213], v153 offset:22528
	ds_read_b128 v[214:217], v153 offset:23552
	global_load_lds_dwordx4 v[190:191], off
	s_add_i32 m0, s10, 0x2000
	s_add_u32 s10, s46, 0x40000
	v_lshl_add_u64 v[218:219], s[46:47], 0, v[132:133]
	s_addc_u32 s11, s47, 0
	s_add_i32 s64, s65, s19
	global_load_lds_dwordx4 v[218:219], off
	v_lshl_add_u64 v[220:221], s[10:11], 0, v[136:137]
	s_mov_b32 m0, s64
	v_lshl_add_u64 v[222:223], s[48:49], 0, v[134:135]
	global_load_lds_dwordx4 v[220:221], off
	v_lshl_add_u64 v[220:221], s[10:11], 0, v[132:133]
	s_add_i32 m0, s64, 0x2000
	s_nop 0
	global_load_lds_dwordx4 v[220:221], off
	v_lshl_add_u64 v[220:221], s[48:49], 0, v[138:139]
	s_mov_b32 m0, s51
	s_nop 0
	global_load_lds_dwordx4 v[220:221], off
	s_mov_b32 m0, s52
	s_nop 0
	global_load_lds_dwordx4 v[222:223], off
	s_waitcnt vmcnt(8)
	s_waitcnt lgkmcnt(0)
	s_setprio 1
	s_barrier
; #define PG8_STAGE(bufoff, gbase, voff) do { _Pragma("unroll") for (int _i = 0; _i < 2; ++_i) \
;         __builtin_amdgcn_global_load_lds((const unsigned*)((const char*)(gbase) + (voff)[_i]), (PG8_LAS unsigned*)(lds + (bufoff) + ldsw + _i * 8192), 16, 0, 0); } while (0)
; #define PG8_LDA(dst, b, h) do { _Pragma("unroll") for (int m = 0; m < 4; ++m) _Pragma("unroll") for (int k = 0; k < 2; ++k) dst[m][k] = *(const PG8_LAS bf16x8*)(lds + PG8_SA(b, h) + aoff + m * 2048 + k * 1024); } while (0)
; #define PG8_LDB(dst, b, h) do { _Pragma("unroll") for (int n = 0; n < 2; ++n) _Pragma("unroll") for (int k = 0; k < 2; ++k) dst[n][k] = *(const PG8_LAS bf16x8*)(lds + PG8_SB(b, h) + boff + n * 2048 + k * 1024); } while (0)
; #define PG8_MMA(ai, bj, At, Bt) do { __builtin_amdgcn_s_setprio(1); _Pragma("unroll") for (int m = 0; m < 4; ++m) _Pragma("unroll") for (int n = 0; n < 2; ++n) _Pragma("unroll") for (int k = 0; k < 2; ++k) \
;         acc[ai][bj][m][n] = __builtin_amdgcn_mfma_f32_16x16x32_bf16(Bt[n][k], At[m][k], acc[ai][bj][m][n], 0, 0, 0); __builtin_amdgcn_s_setprio(0); } while (0)
; #define PG8_WAIT_V(n) asm volatile("s_waitcnt vmcnt(" #n ")" ::: "memory")
; #define PG8_WAIT_L(n) asm volatile("s_waitcnt lgkmcnt(" #n ")" ::: "memory")
; #define PG8_BAR __builtin_amdgcn_s_barrier()
; #define PG8_SCHED __builtin_amdgcn_sched_barrier(0)
; template <class Epi, class Sched, bool ALIGN_EPI = false, bool SP2 = false>
; __device__ __forceinline__ void gemm_phase(PG8_LAS unsigned char* lds, const Gemm g, const Sched& S, const Epi& E) {
;     ...
;             PG8_WAIT_V(8); PG8_WAIT_L(0); PG8_BAR; PG8_MMA(1, 0, At, B0); PG8_MMA(1, 1, At, B1); PG8_BAR; PG8_SCHED;
;             PG8_LDB(B0, 1, 0); PG8_LDB(B1, 1, 1); PG8_SCHED; PG8_LDA(At, 1, 0); PG8_STAGE(PG8_SA(0, 1), a2 + hstep, voffA);
;             PG8_WAIT_V(8); PG8_WAIT_L(0); PG8_BAR; PG8_MMA(0, 0, At, B0); PG8_MMA(0, 1, At, B1); PG8_BAR; PG8_SCHED;
	v_mfma_f32_16x16x32_bf16 v[60:63], v[128:131], v[182:185], v[60:63]
	v_mfma_f32_16x16x32_bf16 v[52:55], v[158:161], v[182:185], v[52:55]
	v_mfma_f32_16x16x32_bf16 v[44:47], v[128:131], v[194:197], v[44:47]
	v_mfma_f32_16x16x32_bf16 v[36:39], v[158:161], v[194:197], v[36:39]
	v_mfma_f32_16x16x32_bf16 v[28:31], v[128:131], v[202:205], v[28:31]
	v_mfma_f32_16x16x32_bf16 v[20:23], v[158:161], v[202:205], v[20:23]
	v_mfma_f32_16x16x32_bf16 v[12:15], v[128:131], v[210:213], v[12:15]
	v_mfma_f32_16x16x32_bf16 v[4:7], v[158:161], v[210:213], v[4:7]
	v_mfma_f32_16x16x32_bf16 v[60:63], v[154:157], v[186:189], v[60:63]
	v_mfma_f32_16x16x32_bf16 v[52:55], v[162:165], v[186:189], v[52:55]
	v_mfma_f32_16x16x32_bf16 v[44:47], v[154:157], v[198:201], v[44:47]
	v_mfma_f32_16x16x32_bf16 v[36:39], v[162:165], v[198:201], v[36:39]
	v_mfma_f32_16x16x32_bf16 v[28:31], v[154:157], v[206:209], v[28:31]
	v_mfma_f32_16x16x32_bf16 v[20:23], v[162:165], v[206:209], v[20:23]
	v_mfma_f32_16x16x32_bf16 v[12:15], v[154:157], v[214:217], v[12:15]
	v_mfma_f32_16x16x32_bf16 v[4:7], v[162:165], v[214:217], v[4:7]
	v_mfma_f32_16x16x32_bf16 v[56:59], v[166:169], v[182:185], v[56:59]
	v_mfma_f32_16x16x32_bf16 v[48:51], v[174:177], v[182:185], v[48:51]
	v_mfma_f32_16x16x32_bf16 v[40:43], v[166:169], v[194:197], v[40:43]
	v_mfma_f32_16x16x32_bf16 v[32:35], v[174:177], v[194:197], v[32:35]
	v_mfma_f32_16x16x32_bf16 v[24:27], v[166:169], v[202:205], v[24:27]
	v_mfma_f32_16x16x32_bf16 v[16:19], v[174:177], v[202:205], v[16:19]
	v_mfma_f32_16x16x32_bf16 v[8:11], v[166:169], v[210:213], v[8:11]
	v_mfma_f32_16x16x32_bf16 v[0:3], v[174:177], v[210:213], v[0:3]
	v_mfma_f32_16x16x32_bf16 v[56:59], v[170:173], v[186:189], v[56:59]
	v_mfma_f32_16x16x32_bf16 v[48:51], v[178:181], v[186:189], v[48:51]
	v_mfma_f32_16x16x32_bf16 v[40:43], v[170:173], v[198:201], v[40:43]
	v_mfma_f32_16x16x32_bf16 v[32:35], v[178:181], v[198:201], v[32:35]
	v_mfma_f32_16x16x32_bf16 v[24:27], v[170:173], v[206:209], v[24:27]
	v_mfma_f32_16x16x32_bf16 v[16:19], v[178:181], v[206:209], v[16:19]
	v_mfma_f32_16x16x32_bf16 v[8:11], v[170:173], v[214:217], v[8:11]
	v_mfma_f32_16x16x32_bf16 v[0:3], v[178:181], v[214:217], v[0:3]
	s_barrier
	s_setprio 0
	s_add_i32 s64, 0, 0x18000
	v_add_u32_e32 v146, s64, v149
	s_add_i32 s65, 0, 0x1c000
	ds_read_b128 v[128:131], v146
	ds_read_b128 v[154:157], v146 offset:1024
	ds_read_b128 v[158:161], v146 offset:2048
	ds_read_b128 v[162:165], v146 offset:3072
	v_add_u32_e32 v146, s65, v149
	ds_read_b128 v[166:169], v146
	ds_read_b128 v[170:173], v146 offset:1024
	ds_read_b128 v[174:177], v146 offset:2048
	ds_read_b128 v[178:181], v146 offset:3072
	s_add_u32 s10, s48, 0x40000
	s_addc_u32 s11, s49, 0
	s_mov_b32 m0, s53
	v_lshl_add_u64 v[224:225], s[10:11], 0, v[138:139]
	ds_read_b128 v[182:185], v153 offset:32768
	ds_read_b128 v[186:189], v153 offset:33792
	ds_read_b128 v[194:197], v153 offset:34816
	ds_read_b128 v[198:201], v153 offset:35840
	ds_read_b128 v[202:205], v153 offset:36864
	ds_read_b128 v[206:209], v153 offset:37888
	ds_read_b128 v[210:213], v153 offset:38912
	ds_read_b128 v[214:217], v153 offset:39936
	global_load_lds_dwordx4 v[224:225], off
	v_lshl_add_u64 v[224:225], s[10:11], 0, v[134:135]
	s_mov_b32 m0, s54
	s_nop 0
	global_load_lds_dwordx4 v[224:225], off
	s_waitcnt vmcnt(8)
	s_waitcnt lgkmcnt(0)
	s_setprio 1
	s_barrier
	v_mfma_f32_16x16x32_bf16 v[124:127], v[128:131], v[182:185], v[124:127]
	v_mfma_f32_16x16x32_bf16 v[116:119], v[158:161], v[182:185], v[116:119]
	v_mfma_f32_16x16x32_bf16 v[108:111], v[128:131], v[194:197], v[108:111]
	v_mfma_f32_16x16x32_bf16 v[100:103], v[158:161], v[194:197], v[100:103]
	v_mfma_f32_16x16x32_bf16 v[92:95], v[128:131], v[202:205], v[92:95]
	v_mfma_f32_16x16x32_bf16 v[84:87], v[158:161], v[202:205], v[84:87]
	v_mfma_f32_16x16x32_bf16 v[76:79], v[128:131], v[210:213], v[76:79]
	v_mfma_f32_16x16x32_bf16 v[68:71], v[158:161], v[210:213], v[68:71]
	v_mfma_f32_16x16x32_bf16 v[124:127], v[154:157], v[186:189], v[124:127]
	v_mfma_f32_16x16x32_bf16 v[116:119], v[162:165], v[186:189], v[116:119]
	v_mfma_f32_16x16x32_bf16 v[108:111], v[154:157], v[198:201], v[108:111]
	v_mfma_f32_16x16x32_bf16 v[100:103], v[162:165], v[198:201], v[100:103]
	v_mfma_f32_16x16x32_bf16 v[92:95], v[154:157], v[206:209], v[92:95]
	v_mfma_f32_16x16x32_bf16 v[84:87], v[162:165], v[206:209], v[84:87]
	v_mfma_f32_16x16x32_bf16 v[76:79], v[154:157], v[214:217], v[76:79]
	v_mfma_f32_16x16x32_bf16 v[68:71], v[162:165], v[214:217], v[68:71]
	v_mfma_f32_16x16x32_bf16 v[120:123], v[166:169], v[182:185], v[120:123]
	v_mfma_f32_16x16x32_bf16 v[112:115], v[174:177], v[182:185], v[112:115]
	v_mfma_f32_16x16x32_bf16 v[104:107], v[166:169], v[194:197], v[104:107]
	v_mfma_f32_16x16x32_bf16 v[96:99], v[174:177], v[194:197], v[96:99]
	v_mfma_f32_16x16x32_bf16 v[88:91], v[166:169], v[202:205], v[88:91]
	v_mfma_f32_16x16x32_bf16 v[80:83], v[174:177], v[202:205], v[80:83]
	v_mfma_f32_16x16x32_bf16 v[72:75], v[166:169], v[210:213], v[72:75]
	v_mfma_f32_16x16x32_bf16 v[64:67], v[174:177], v[210:213], v[64:67]
	v_mfma_f32_16x16x32_bf16 v[120:123], v[170:173], v[186:189], v[120:123]
	v_mfma_f32_16x16x32_bf16 v[112:115], v[178:181], v[186:189], v[112:115]
	v_mfma_f32_16x16x32_bf16 v[104:107], v[170:173], v[198:201], v[104:107]
	v_mfma_f32_16x16x32_bf16 v[96:99], v[178:181], v[198:201], v[96:99]
	v_mfma_f32_16x16x32_bf16 v[88:91], v[170:173], v[206:209], v[88:91]
	v_mfma_f32_16x16x32_bf16 v[80:83], v[178:181], v[206:209], v[80:83]
	v_mfma_f32_16x16x32_bf16 v[72:75], v[170:173], v[214:217], v[72:75]
	v_mfma_f32_16x16x32_bf16 v[64:67], v[178:181], v[214:217], v[64:67]
	s_barrier
; #define PG8_STAGE(bufoff, gbase, voff) do { _Pragma("unroll") for (int _i = 0; _i < 2; ++_i) \
;         __builtin_amdgcn_global_load_lds((const unsigned*)((const char*)(gbase) + (voff)[_i]), (PG8_LAS unsigned*)(lds + (bufoff) + ldsw + _i * 8192), 16, 0, 0); } while (0)
; #define PG8_LDA(dst, b, h) do { _Pragma("unroll") for (int m = 0; m < 4; ++m) _Pragma("unroll") for (int k = 0; k < 2; ++k) dst[m][k] = *(const PG8_LAS bf16x8*)(lds + PG8_SA(b, h) + aoff + m * 2048 + k * 1024); } while (0)
; #define PG8_MMA(ai, bj, At, Bt) do { __builtin_amdgcn_s_setprio(1); _Pragma("unroll") for (int m = 0; m < 4; ++m) _Pragma("unroll") for (int n = 0; n < 2; ++n) _Pragma("unroll") for (int k = 0; k < 2; ++k) \
;         acc[ai][bj][m][n] = __builtin_amdgcn_mfma_f32_16x16x32_bf16(Bt[n][k], At[m][k], acc[ai][bj][m][n], 0, 0, 0); __builtin_amdgcn_s_setprio(0); } while (0)
; #define PG8_WAIT_V(n) asm volatile("s_waitcnt vmcnt(" #n ")" ::: "memory")
; #define PG8_WAIT_L(n) asm volatile("s_waitcnt lgkmcnt(" #n ")" ::: "memory")
; #define PG8_BAR __builtin_amdgcn_s_barrier()
; #define PG8_SCHED __builtin_amdgcn_sched_barrier(0)
; template <class Epi, class Sched, bool ALIGN_EPI = false, bool SP2 = false>
; __device__ __forceinline__ void gemm_phase(PG8_LAS unsigned char* lds, const Gemm g, const Sched& S, const Epi& E) {
;     ...
;         for (int t = 0; t < nt; t += 2) {
;             const bool last = (t == nt - 2);
;             const char* a1 = cA + (size_t)(t + 1) * kstep;
;     ...
;             PG8_LDA(At, 1, 1); PG8_STAGE(PG8_SB(1, 0), b3, voffB); PG8_STAGE(PG8_SB(1, 1), b3 + hstep, voffB); PG8_STAGE(PG8_SA(1, 0), a3, voffA);
;             PG8_WAIT_V(8); PG8_WAIT_L(0); PG8_BAR; PG8_MMA(1, 0, At, B0); PG8_MMA(1, 1, At, B1); PG8_BAR; PG8_SCHED;
	s_setprio 0
	s_add_i32 s10, s64, s19
	v_lshl_add_u64 v[190:191], v[190:191], 0, s[36:37]
	s_mov_b32 m0, s10
	ds_read_b128 v[182:185], v153 offset:49152
	ds_read_b128 v[186:189], v153 offset:50176
	ds_read_b128 v[194:197], v153 offset:51200
	ds_read_b128 v[198:201], v153 offset:52224
	ds_read_b128 v[202:205], v153 offset:53248
	ds_read_b128 v[206:209], v153 offset:54272
	ds_read_b128 v[210:213], v153 offset:55296
	ds_read_b128 v[214:217], v153 offset:56320
	global_load_lds_dwordx4 v[190:191], off
	s_add_i32 m0, s10, 0x2000
	s_add_u32 s10, s46, 0x40080
	v_lshl_add_u64 v[190:191], v[218:219], 0, s[36:37]
	s_addc_u32 s11, s47, 0
	s_add_i32 s46, s65, s19
	global_load_lds_dwordx4 v[190:191], off
	v_lshl_add_u64 v[190:191], s[10:11], 0, v[136:137]
	s_mov_b32 m0, s46
	s_nop 0
	global_load_lds_dwordx4 v[190:191], off
	v_lshl_add_u64 v[190:191], s[10:11], 0, v[132:133]
	s_add_i32 m0, s46, 0x2000
	s_nop 0
	global_load_lds_dwordx4 v[190:191], off
	v_lshl_add_u64 v[190:191], v[220:221], 0, s[36:37]
	s_mov_b32 m0, s20
	s_nop 0
	global_load_lds_dwordx4 v[190:191], off
	v_lshl_add_u64 v[190:191], v[222:223], 0, s[36:37]
	s_mov_b32 m0, s55
	s_nop 0
	global_load_lds_dwordx4 v[190:191], off
	s_waitcnt vmcnt(8)
	s_waitcnt lgkmcnt(0)
	s_setprio 1
	s_barrier
	v_mfma_f32_16x16x32_bf16 v[60:63], v[128:131], v[182:185], v[60:63]
	v_mfma_f32_16x16x32_bf16 v[52:55], v[158:161], v[182:185], v[52:55]
	v_mfma_f32_16x16x32_bf16 v[44:47], v[128:131], v[194:197], v[44:47]
	v_mfma_f32_16x16x32_bf16 v[36:39], v[158:161], v[194:197], v[36:39]
	v_mfma_f32_16x16x32_bf16 v[28:31], v[128:131], v[202:205], v[28:31]
	v_mfma_f32_16x16x32_bf16 v[20:23], v[158:161], v[202:205], v[20:23]
	v_mfma_f32_16x16x32_bf16 v[12:15], v[128:131], v[210:213], v[12:15]
	v_mfma_f32_16x16x32_bf16 v[4:7], v[158:161], v[210:213], v[4:7]
	v_mfma_f32_16x16x32_bf16 v[60:63], v[154:157], v[186:189], v[60:63]
	v_mfma_f32_16x16x32_bf16 v[52:55], v[162:165], v[186:189], v[52:55]
	v_mfma_f32_16x16x32_bf16 v[44:47], v[154:157], v[198:201], v[44:47]
	v_mfma_f32_16x16x32_bf16 v[36:39], v[162:165], v[198:201], v[36:39]
	v_mfma_f32_16x16x32_bf16 v[28:31], v[154:157], v[206:209], v[28:31]
	v_mfma_f32_16x16x32_bf16 v[20:23], v[162:165], v[206:209], v[20:23]
	v_mfma_f32_16x16x32_bf16 v[12:15], v[154:157], v[214:217], v[12:15]
	v_mfma_f32_16x16x32_bf16 v[4:7], v[162:165], v[214:217], v[4:7]
	v_mfma_f32_16x16x32_bf16 v[56:59], v[166:169], v[182:185], v[56:59]
	v_mfma_f32_16x16x32_bf16 v[48:51], v[174:177], v[182:185], v[48:51]
	v_mfma_f32_16x16x32_bf16 v[40:43], v[166:169], v[194:197], v[40:43]
	v_mfma_f32_16x16x32_bf16 v[32:35], v[174:177], v[194:197], v[32:35]
	v_mfma_f32_16x16x32_bf16 v[24:27], v[166:169], v[202:205], v[24:27]
	v_mfma_f32_16x16x32_bf16 v[16:19], v[174:177], v[202:205], v[16:19]
	v_mfma_f32_16x16x32_bf16 v[8:11], v[166:169], v[210:213], v[8:11]
	v_mfma_f32_16x16x32_bf16 v[0:3], v[174:177], v[210:213], v[0:3]
	v_mfma_f32_16x16x32_bf16 v[56:59], v[170:173], v[186:189], v[56:59]
	v_mfma_f32_16x16x32_bf16 v[48:51], v[178:181], v[186:189], v[48:51]
	v_mfma_f32_16x16x32_bf16 v[40:43], v[170:173], v[198:201], v[40:43]
	v_mfma_f32_16x16x32_bf16 v[32:35], v[178:181], v[198:201], v[32:35]
	v_mfma_f32_16x16x32_bf16 v[24:27], v[170:173], v[206:209], v[24:27]
	v_mfma_f32_16x16x32_bf16 v[16:19], v[178:181], v[206:209], v[16:19]
	v_mfma_f32_16x16x32_bf16 v[8:11], v[170:173], v[214:217], v[8:11]
	v_mfma_f32_16x16x32_bf16 v[0:3], v[178:181], v[214:217], v[0:3]
	s_barrier
	s_setprio 0
	s_add_i32 s63, s63, 2
	s_add_u32 s44, s44, 0x100
	s_addc_u32 s45, s45, 0
	s_add_u32 s61, s61, 0x100
	s_addc_u32 s62, s62, 0
	s_cmp_gt_u32 s63, 13
	s_cbranch_scc0 .LBB0_577
	s_and_b64 vcc, exec, s[24:25]
	s_cbranch_vccz .LBB0_580
	s_barrier
